# small-M path of P4/P6 re-tiled: all 256 workgroups compute 16 rows x 32 cols (K split over waves, owner wave runs epilogue) instead of 32 workgroups x 128 rows; on top of v23
# speedup vs baseline: 1.0037x; 1.0037x over previous
; #define LAS __attribute__((address_space(3)))
; __device__ __forceinline__ SmallId small_id() { int tid = threadIdx.x; asm volatile("" : "+v"(tid)); SmallId i; i.w = __builtin_amdgcn_readfirstlane(tid >> 6); i.fr = tid & 15; i.fq = (tid & 63) >> 4; i.row = MP + 16 * i.w + i.fr; return i; }
; template <int KSTEPS  >
; __device__ __forceinline__ void small_mma_ksplit(f32x4 (&acc)[2], const bf16_t* A, int lda, const bf16_t* Bt, int ldb, int n0, LAS unsigned char* lds, const SmallId& id) {
;     const int lane = id.fq * 16 + id.fr, k0 = id.w * (KSTEPS * 32);
;     f32x4 part[8][2];
; #pragma unroll
;     for (int rb = 0; rb < 8; ++rb) { part[rb][0] = (f32x4){0.f, 0.f, 0.f, 0.f}; part[rb][1] = part[rb][0]; }
;     const bf16_t* ap = A + (size_t)(MP + id.fr) * lda + k0 + 8 * id.fq;
;     const bf16_t* bp = Bt + (size_t)(n0 + id.fr) * ldb + k0 + 8 * id.fq;
; template <bool RES_F32, bool OUT_F32, int KSTEPS>
; __device__ __forceinline__ void small_res(const Params& p, LAS unsigned char* lds, const bf16_t* A, int lda, const bf16_t* Bt, int K, float* ssq_next, int G, int bx) {
;     const SmallId id = small_id();
;     bf16_t* XB = (bf16_t*)(p.ws + WS_XB);
;     for (int ts = G - 1 - bx; ts < DM / 32; ts += G) {
;         const int n0 = ts * 32; f32x4 acc[2] = {(f32x4){0.f, 0.f, 0.f, 0.f}, (f32x4){0.f, 0.f, 0.f, 0.f}};
.LBB0_858:
	s_or_b64 exec, exec, s[0:1]
	v_readlane_b32 s0, v246, 16
	v_readlane_b32 s2, v246, 13
	s_add_u32 s40, s0, 0x880000
	v_readlane_b32 s0, v246, 17
	v_readlane_b32 s3, v246, 14
	s_addc_u32 s41, s0, 0
	s_and_b64 vcc, exec, s[2:3]
	v_readlane_b32 s2, v247, 8
	v_readlane_b32 s3, v247, 9
	s_mov_b64 s[0:1], -1
	s_waitcnt lgkmcnt(0)
	v_cndmask_b32_e64 v0, 0, 1, s[2:3]
	v_cmp_ne_u32_e64 s[2:3], 1, v0
	s_barrier
	s_nop 0
	v_writelane_b32 v246, s2, 22
	s_nop 1
	v_writelane_b32 v246, s3, 23
	s_cbranch_vccz .LBB0_903
	v_readlane_b32 s0, v246, 22
	s_add_u32 s2, s86, 0x60c00
	v_mov_b32_e32 v0, v222
	v_readlane_b32 s1, v246, 23
	s_addc_u32 s3, s87, 0
	s_and_b64 vcc, exec, s[0:1]
	v_readfirstlane_b32 s0, v0
	s_ashr_i32 s7, s0, 6
	s_lshl_b32 s0, s7, 4
	v_and_b32_e32 v4, 15, v0
	s_add_i32 s0, s0, 0x8000
	v_or_b32_e32 v2, s0, v4
	v_bfe_u32 v5, v0, 4, 2
	s_lshl_b32 s0, s7, 7
	s_lshl_b32 s8, s7, 14
	v_lshlrev_b32_e32 v0, 4, v0
	s_lshl_b32 s7, s7, 11
	s_add_i32 s8, s8, 0
	v_and_b32_e32 v0, 0x3f0, v0
	s_add_i32 s7, s7, 0
	v_add_u32_e32 v76, s8, v0
	s_add_i32 s8, s7, 0x10400
	s_ashr_i32 s1, s0, 31
	v_add_u32_e32 v79, s8, v0
	s_add_i32 s8, s7, 0x14400
	v_add_u32_e32 v77, s7, v0
	v_add_u32_e32 v81, s8, v0
	s_add_i32 s8, s7, 0x18400
	s_add_i32 s7, s7, 0x1c400
	s_lshl_b64 s[0:1], s[0:1], 1
	s_add_u32 s0, s86, s0
	v_add_u32_e32 v85, s7, v0
	s_addc_u32 s1, s87, s1
	s_mul_i32 s7, s93, 0x1b00000
	v_add_u32_e32 v83, s8, v0
	s_add_u32 s8, s0, s7
	v_ashrrev_i32_e32 v3, 31, v2
	v_lshlrev_b32_e32 v96, 4, v5
	s_addc_u32 s9, s1, 0
	v_lshlrev_b64 v[0:1], 11, v[2:3]
	v_lshl_add_u64 v[68:69], s[8:9], 0, v[96:97]
	v_readlane_b32 s7, v246, 8
	s_lshr_b32 s7, s7, 3
	s_lshl_b32 s7, s7, 5
	v_lshl_or_b32 v96, v4, 11, v96
	v_add_u32_e32 v78, 0x10000, v77
	v_add_u32_e32 v80, 0x14000, v77
	v_add_u32_e32 v82, 0x18000, v77
	v_add_u32_e32 v84, 0x1c000, v77
	v_lshlrev_b32_e32 v86, 2, v5
	v_lshl_add_u64 v[64:65], s[90:91], 0, v[0:1]
	v_cmp_eq_u32_e32 vcc, 0, v5
	v_lshl_add_u64 v[66:67], v[2:3], 2, s[2:3]
	v_add_u32_e32 v70, s7, v4
	v_lshl_add_u64 v[72:73], s[0:1], 0, v[96:97]
	v_readlane_b32 s7, v246, 8
	s_lshr_b32 s7, s7, 3
	s_branch .LBB0_862

; template <int KSTEPS  >
; __device__ __forceinline__ void small_mma_ksplit(f32x4 (&acc)[2], const bf16_t* A, int lda, const bf16_t* Bt, int ldb, int n0, LAS unsigned char* lds, const SmallId& id) {
;     const int lane = id.fq * 16 + id.fr, k0 = id.w * (KSTEPS * 32);
;     f32x4 part[8][2];
; #pragma unroll
;     for (int rb = 0; rb < 8; ++rb) { part[rb][0] = (f32x4){0.f, 0.f, 0.f, 0.f}; part[rb][1] = part[rb][0]; }
;     const bf16_t* ap = A + (size_t)(MP + id.fr) * lda + k0 + 8 * id.fq;
;     const bf16_t* bp = Bt + (size_t)(n0 + id.fr) * ldb + k0 + 8 * id.fq;
; #pragma unroll 1
;     for (int ks = 0; ks < KSTEPS; ++ks) {
;         bf16x8 a[8], b[2];
; #pragma unroll
;         for (int rb = 0; rb < 8; ++rb) a[rb] = *(const bf16x8*)(ap + (size_t)(16 * rb) * lda + 32 * ks);
;         b[0] = *(const bf16x8*)(bp + 32 * ks); b[1] = *(const bf16x8*)(bp + (size_t)16 * ldb + 32 * ks);
; #pragma unroll
;         for (int rb = 0; rb < 8; ++rb) { part[rb][0] = __builtin_amdgcn_mfma_f32_16x16x32_bf16(b[0], a[rb], part[rb][0], 0, 0, 0); part[rb][1] = __builtin_amdgcn_mfma_f32_16x16x32_bf16(b[1], a[rb], part[rb][1], 0, 0, 0); }
;     }
;     LAS f32x4* red = (LAS f32x4*)lds;
; #pragma unroll
;     for (int rb = 0; rb < 8; ++rb) { red[((id.w * 8 + rb) * 2 + 0) * 64 + lane] = part[rb][0]; red[((id.w * 8 + rb) * 2 + 1) * 64 + lane] = part[rb][1]; }
;     asm volatile("s_waitcnt lgkmcnt(0)" ::: "memory"); __syncthreads();
;     acc[0] = (f32x4){0.f, 0.f, 0.f, 0.f}; acc[1] = acc[0];
; #pragma unroll
;     for (int w2 = 0; w2 < 8; ++w2) { acc[0] += red[((w2 * 8 + id.w) * 2 + 0) * 64 + lane]; acc[1] += red[((w2 * 8 + id.w) * 2 + 1) * 64 + lane]; }
;     asm volatile("s_waitcnt lgkmcnt(0)" ::: "memory"); __syncthreads();
; template <bool RES_F32, bool OUT_F32, int KSTEPS>
; __device__ __forceinline__ void small_res(const Params& p, LAS unsigned char* lds, const bf16_t* A, int lda, const bf16_t* Bt, int K, float* ssq_next, int G, int bx) {
;     ...
;         float s = 0.f;
; #pragma unroll
;         for (int nb = 0; nb < 2; ++nb) { const int col = n0 + 16 * nb + 4 * id.fq;
;             f32x4 r;
;             if (RES_F32) r = *(const f32x4*)(p.xs + (size_t)(id.row - MP) * DM + col);
;             else { const u32x2 w = *(const u32x2*)(XB + (size_t)id.row * DM + col); r = (f32x4){bf_lo(w.x), bf_hi(w.x), bf_lo(w.y), bf_hi(w.y)}; }
;             const f32x4 x = r + acc[nb];
.LBB0_863:
	s_waitcnt lgkmcnt(0)
	v_readlane_b32 s8, v246, 8
	v_readfirstlane_b32 s32, v222
	s_and_b32 s8, s8, 7
	s_lshr_b32 s32, s32, 6
	s_cmp_eq_u32 s32, s8
	s_cselect_b32 s32, 1, 0
	s_lshl_b32 s9, s8, 11
	v_add_u32_e32 v68, s9, v76
	s_sub_i32 s9, s11, s10
	s_mul_i32 s8, s8, s9
	s_add_i32 s8, s8, s10
	s_mov_b32 s9, 0
	v_lshl_add_u64 v[70:71], v[72:73], 0, s[8:9]
	s_mov_b32 s8, s18
	v_lshl_add_u64 v[88:89], v[74:75], 0, s[8:9]
	s_mov_b32 s8, s19
	v_lshl_add_u64 v[90:91], v[74:75], 0, s[8:9]
	global_load_dwordx4 v[92:95], v[70:71], off
	global_load_dwordx4 v[98:101], v[88:89], off
	global_load_dwordx4 v[102:105], v[90:91], off
	global_load_dwordx4 v[106:109], v[70:71], off offset:64
	global_load_dwordx4 v[110:113], v[88:89], off offset:64
	global_load_dwordx4 v[114:117], v[90:91], off offset:64
	global_load_dwordx4 v[118:121], v[70:71], off offset:128
	global_load_dwordx4 v[122:125], v[88:89], off offset:128
	global_load_dwordx4 v[126:129], v[90:91], off offset:128
	global_load_dwordx4 v[130:133], v[70:71], off offset:192
	global_load_dwordx4 v[134:137], v[88:89], off offset:192
	global_load_dwordx4 v[138:141], v[90:91], off offset:192
	s_waitcnt vmcnt(9)
	v_mfma_f32_16x16x32_bf16 v[36:39], v[98:101], v[92:95], v[36:39]
	v_mfma_f32_16x16x32_bf16 v[24:27], v[102:105], v[92:95], v[24:27]
	s_waitcnt vmcnt(6)
	v_mfma_f32_16x16x32_bf16 v[36:39], v[110:113], v[106:109], v[36:39]
	v_mfma_f32_16x16x32_bf16 v[24:27], v[114:117], v[106:109], v[24:27]
	s_waitcnt vmcnt(3)
	v_mfma_f32_16x16x32_bf16 v[36:39], v[122:125], v[118:121], v[36:39]
	v_mfma_f32_16x16x32_bf16 v[24:27], v[126:129], v[118:121], v[24:27]
	s_waitcnt vmcnt(0)
	v_mfma_f32_16x16x32_bf16 v[36:39], v[134:137], v[130:133], v[36:39]
	v_mfma_f32_16x16x32_bf16 v[24:27], v[138:141], v[130:133], v[24:27]
	s_nop 7
	s_nop 1
	ds_write_b128 v68, v[36:39]
	ds_write_b128 v68, v[24:27] offset:1024
	s_waitcnt lgkmcnt(0)
	s_waitcnt lgkmcnt(0)
	s_barrier
	ds_read_b128 v[0:3], v77
	s_waitcnt lgkmcnt(0)
	v_pk_add_f32 v[4:5], v[2:3], 0 op_sel_hi:[1,0]
	v_pk_add_f32 v[6:7], v[0:1], 0 op_sel_hi:[1,0]
	ds_read_b128 v[0:3], v77 offset:1024
	s_waitcnt lgkmcnt(0)
	v_pk_add_f32 v[8:9], v[2:3], 0 op_sel_hi:[1,0]
	v_pk_add_f32 v[10:11], v[0:1], 0 op_sel_hi:[1,0]
	ds_read_b128 v[0:3], v77 offset:16384
	s_waitcnt lgkmcnt(0)
	v_pk_add_f32 v[4:5], v[4:5], v[2:3]
	v_pk_add_f32 v[6:7], v[6:7], v[0:1]
	ds_read_b128 v[0:3], v77 offset:17408
	s_waitcnt lgkmcnt(0)
	v_pk_add_f32 v[8:9], v[8:9], v[2:3]
	v_pk_add_f32 v[10:11], v[10:11], v[0:1]
	ds_read_b128 v[0:3], v77 offset:32768
	s_waitcnt lgkmcnt(0)
	v_pk_add_f32 v[4:5], v[4:5], v[2:3]
	v_pk_add_f32 v[6:7], v[6:7], v[0:1]
	ds_read_b128 v[0:3], v77 offset:33792
	s_waitcnt lgkmcnt(0)
	v_pk_add_f32 v[8:9], v[8:9], v[2:3]
	v_pk_add_f32 v[10:11], v[10:11], v[0:1]
	ds_read_b128 v[0:3], v77 offset:49152
	s_waitcnt lgkmcnt(0)
	v_pk_add_f32 v[4:5], v[4:5], v[2:3]
	v_pk_add_f32 v[6:7], v[6:7], v[0:1]
	ds_read_b128 v[0:3], v77 offset:50176
	s_waitcnt lgkmcnt(0)
	v_pk_add_f32 v[8:9], v[8:9], v[2:3]
	v_pk_add_f32 v[10:11], v[10:11], v[0:1]
	ds_read_b128 v[0:3], v78
	s_waitcnt lgkmcnt(0)
	v_pk_add_f32 v[4:5], v[4:5], v[2:3]
	v_pk_add_f32 v[6:7], v[6:7], v[0:1]
	ds_read_b128 v[0:3], v79
	s_waitcnt lgkmcnt(0)
	v_pk_add_f32 v[8:9], v[8:9], v[2:3]
	v_pk_add_f32 v[10:11], v[10:11], v[0:1]
	ds_read_b128 v[0:3], v80
	s_waitcnt lgkmcnt(0)
	v_pk_add_f32 v[4:5], v[4:5], v[2:3]
	v_pk_add_f32 v[6:7], v[6:7], v[0:1]
	ds_read_b128 v[0:3], v81
	s_waitcnt lgkmcnt(0)
	v_pk_add_f32 v[8:9], v[8:9], v[2:3]
	v_pk_add_f32 v[10:11], v[10:11], v[0:1]
	ds_read_b128 v[0:3], v82
	s_waitcnt lgkmcnt(0)
	v_pk_add_f32 v[4:5], v[4:5], v[2:3]
	v_pk_add_f32 v[6:7], v[6:7], v[0:1]
	ds_read_b128 v[0:3], v83
	s_waitcnt lgkmcnt(0)
	v_pk_add_f32 v[8:9], v[8:9], v[2:3]
	v_pk_add_f32 v[10:11], v[10:11], v[0:1]
	ds_read_b128 v[0:3], v84
	s_waitcnt lgkmcnt(0)
	v_pk_add_f32 v[4:5], v[4:5], v[2:3]
	v_pk_add_f32 v[6:7], v[6:7], v[0:1]
	ds_read_b128 v[0:3], v85
	s_waitcnt lgkmcnt(0)
	s_waitcnt lgkmcnt(0)
	s_barrier
	s_mul_i32 exec_lo, s32, -1
	s_mov_b32 exec_hi, exec_lo
	v_pk_add_f32 v[2:3], v[8:9], v[2:3]
	v_lshl_or_b32 v8, s7, 5, v86
	v_ashrrev_i32_e32 v9, 31, v8
	v_lshl_add_u64 v[8:9], v[8:9], 1, v[64:65]
	v_pk_add_f32 v[0:1], v[10:11], v[0:1]
	global_load_dwordx2 v[10:11], v[8:9], off
	s_waitcnt vmcnt(0) lgkmcnt(0)
	v_lshlrev_b32_e32 v12, 16, v10
	v_and_b32_e32 v13, 0xffff0000, v10
	v_lshlrev_b32_e32 v10, 16, v11
	v_and_b32_e32 v11, 0xffff0000, v11
	v_pk_add_f32 v[4:5], v[4:5], v[10:11]
	v_pk_add_f32 v[6:7], v[6:7], v[12:13]
	s_nop 0
	v_cvt_pk_bf16_f32 v10, v6, v7
	v_cvt_pk_bf16_f32 v11, v4, v5
	v_mul_f32_e32 v7, v7, v7
	v_mul_f32_e32 v5, v5, v5
	v_fmac_f32_e32 v7, v6, v6
	v_fmac_f32_e32 v5, v4, v4
	global_store_dwordx2 v[8:9], v[10:11], off
	v_add_f32_e32 v10, v7, v5
	global_load_dwordx2 v[4:5], v[8:9], off offset:32
	s_waitcnt vmcnt(0) lgkmcnt(0)
	v_lshlrev_b32_e32 v6, 16, v4
	v_and_b32_e32 v7, 0xffff0000, v4
	v_lshlrev_b32_e32 v4, 16, v5
	v_and_b32_e32 v5, 0xffff0000, v5
	v_pk_add_f32 v[0:1], v[0:1], v[6:7]
	v_pk_add_f32 v[2:3], v[2:3], v[4:5]
	v_cvt_pk_bf16_f32 v4, v0, v1
	v_mul_f32_e32 v1, v1, v1
	v_fmac_f32_e32 v1, v0, v0
	v_mul_f32_e32 v0, v3, v3
	v_cvt_pk_bf16_f32 v5, v2, v3
	v_fmac_f32_e32 v0, v2, v2
	v_and_b32_e32 v2, 64, v225
	v_add_f32_e32 v0, v1, v0
	v_xor_b32_e32 v1, 16, v225
	v_add_u32_e32 v2, 64, v2
	v_cmp_lt_i32_e64 s[0:1], v1, v2
	v_add_f32_e32 v0, v10, v0
	global_store_dwordx2 v[8:9], v[4:5], off offset:32
	v_cndmask_b32_e64 v1, v225, v1, s[0:1]
	v_lshlrev_b32_e32 v1, 2, v1
	ds_bpermute_b32 v1, v1, v0
	s_waitcnt lgkmcnt(0)
	v_add_f32_e32 v0, v0, v1
	v_xor_b32_e32 v1, 32, v225
	v_cmp_lt_i32_e64 s[0:1], v1, v2
	s_nop 1
	v_cndmask_b32_e64 v1, v225, v1, s[0:1]
	v_lshlrev_b32_e32 v1, 2, v1
	ds_bpermute_b32 v1, v1, v0
	s_and_saveexec_b64 s[0:1], vcc
	s_cbranch_execz .LBB0_861
	s_waitcnt lgkmcnt(0)
	v_add_f32_e32 v0, v0, v1
	global_atomic_add_f32 v[66:67], v0, off
	s_branch .LBB0_861
; #define PG8_STAGE(bufoff, gbase, voff) do { _Pragma("unroll") for (int _i = 0; _i < 2; ++_i) \
;         __builtin_amdgcn_global_load_lds((const unsigned*)((const char*)(gbase) + (voff)[_i]), (LAS unsigned*)(lds + (bufoff) + ldsw + _i * 8192), 16, 0, 0); } while (0)
; #define PG8_BAR __builtin_amdgcn_s_barrier()
;     __device__ __forceinline__ bool next(int i, Unit& u) const { u.z = 0; return o.tile(i, u); }
;     __device__ __forceinline__ long a_off(const Unit& u) const { return (long)u.pm * tA; }
;     __device__ __forceinline__ long b_off(const Unit& u) const { return (long)u.pn * tB; }
;     __device__ __forceinline__ bool next(int i, Unit& u) const { u.z = i & 1; return o.tile(i >> 1, u); }
; template <class Epi, class Sched>
; __device__ __forceinline__ void gemm_phase(LAS unsigned char* lds, const Gemm g, const Sched& S, const Epi& E) {
;     ...
;     const int wid = __builtin_amdgcn_readfirstlane(tid >> 6), lane = tid & 63, wr = wid >> 2, wc = wid & 3, fr = lane & 15, fq = lane >> 4;
;     const int K = g.K, nt = K / BK;
;     unsigned voffA[2], voffB[2];
; #pragma unroll
;     for (int i = 0; i < 2; ++i) { int R, C; stage_rc(tid * 16 + i * 8192, R, C); const int Rb = Epi::PERM ? ((R & ~31) + perm32(R & 31)) : R;
;         voffA[i] = (unsigned)(R * g.lda + C) * 2u; voffB[i] = (unsigned)(Rb * g.ldb + C) * 2u; }
;     const size_t kstep = (size_t)(BK * 2);
;     const size_t hstepA = (size_t)HALF * g.lda * 2, hstepB = (size_t)HALF * g.ldb * 2;
;     const unsigned ldsw = (unsigned)wid * 1024u;
;     const int aoff = lds_byte(wr * 64 + fr, fq * 8), boff = lds_byte(wc * 32 + fr, fq * 8);
;     ...
;     Unit cur, nxt; int ui = 0;
;     if (!S.next(0, cur)) return;
;     f32x4 acc[2][2][4][2];
; #pragma unroll
;     for (int a = 0; a < 2; ++a)
; #pragma unroll
;         for (int b = 0; b < 2; ++b)
; #pragma unroll
;             for (int m = 0; m < 4; ++m)
; #pragma unroll
;                 for (int n = 0; n < 2; ++n) acc[a][b][m][n] = (f32x4){0.f, 0.f, 0.f, 0.f};
;     bf16x8 At[4][2], B0[2][2], B1[2][2];
;     const char* cA = (const char*)g.A + S.a_off(cur); const char* cB = (const char*)g.Bt + S.b_off(cur);
;     PG8_STAGE(PG8_SB(0, 0), cB, voffB); PG8_STAGE(PG8_SB(0, 1), cB + hstepB, voffB); PG8_STAGE(PG8_SA(0, 0), cA, voffA); PG8_STAGE(PG8_SA(0, 1), cA + hstepA, voffA);
;     if (wr == 1) PG8_BAR;
.LBB0_866:
	s_mov_b64 exec, -1
	v_readlane_b32 s0, v246, 24
	v_mov_b32_e32 v6, v222
	v_readlane_b32 s1, v246, 25
	s_and_b64 vcc, exec, s[0:1]
	v_readfirstlane_b32 s10, v6
	s_cbranch_vccnz .LBB0_902
	v_lshlrev_b32_e32 v3, 4, v6
	s_waitcnt lgkmcnt(0)
	v_add_u32_e32 v1, 0x2000, v3
	v_ashrrev_i32_e32 v0, 31, v1
	v_lshrrev_b32_e32 v0, 22, v0
	v_add_u32_e32 v0, v1, v0
	v_ashrrev_i32_e32 v0, 10, v0
	v_mul_i32_i24_e32 v2, 0x400, v0
	v_sub_u32_e32 v1, v1, v2
	v_lshrrev_b32_e32 v2, 4, v1
	v_bitop3_b32 v2, v2, v1, 32 bitop3:0x6c
	v_ashrrev_i32_e32 v1, 31, v2
	v_lshrrev_b32_e32 v1, 26, v1
	v_add_u32_e32 v4, v2, v1
	v_lshlrev_b32_e32 v5, 3, v0
	v_ashrrev_i32_e32 v1, 6, v4
	v_and_b32_e32 v5, -16, v5
	v_add_u32_e32 v5, v1, v5
	v_and_b32_e32 v7, 3, v1
	s_mov_b32 s0, 0x1fffe0
	v_lshrrev_b32_e32 v8, 2, v5
	v_lshlrev_b32_e32 v9, 1, v5
	v_and_b32_e32 v4, 0xc0, v4
	v_and_or_b32 v7, v5, s0, v7
	v_and_b32_e32 v8, 4, v8
	v_and_b32_e32 v9, 24, v9
	v_sub_u32_e32 v2, v2, v4
	v_or3_b32 v7, v7, v8, v9
	v_lshlrev_b32_e32 v8, 5, v0
	v_ashrrev_i16_sdwa v2, v224, sext(v2) dst_sel:DWORD dst_unused:UNUSED_PAD src0_sel:DWORD src1_sel:BYTE_0
	v_and_b32_e32 v8, 32, v8
	v_bfe_i32 v2, v2, 0, 16
	v_add_lshl_u32 v4, v8, v2, 1
	v_lshl_add_u32 v206, v7, 11, v4
	v_lshl_add_u32 v208, v5, 11, v4
	v_bfe_i32 v4, v6, 27, 1
	v_lshrrev_b32_e32 v4, 22, v4
	v_add_u32_e32 v4, v3, v4
	v_and_b32_e32 v4, 0xfffffc00, v4
	v_sub_u32_e32 v3, v3, v4
	v_lshrrev_b32_e32 v4, 4, v3
	v_bitop3_b32 v5, v4, v3, 32 bitop3:0x6c
	v_ashrrev_i32_e32 v4, 31, v6
	v_lshrrev_b32_e32 v4, 26, v4
	v_ashrrev_i32_e32 v3, 31, v5
	v_add_u32_e32 v4, v6, v4
	v_lshrrev_b32_e32 v3, 26, v3
	v_ashrrev_i32_e32 v4, 6, v4
	v_add_u32_e32 v7, v5, v3
	v_lshlrev_b32_e32 v8, 3, v4
	v_ashrrev_i32_e32 v3, 6, v7
	v_and_b32_e32 v8, -16, v8
	v_add_u32_e32 v8, v3, v8
	v_and_b32_e32 v9, 3, v3
	v_lshrrev_b32_e32 v10, 2, v8
	v_lshlrev_b32_e32 v11, 1, v8
	v_and_b32_e32 v7, 0xc0, v7
	s_ashr_i32 s11, s10, 6
	v_and_or_b32 v9, v8, s0, v9
	v_and_b32_e32 v10, 4, v10
	v_and_b32_e32 v11, 24, v11
	v_sub_u32_e32 v5, v5, v7
	s_ashr_i32 s12, s10, 8
	s_lshl_b32 s7, s11, 10
	v_or3_b32 v9, v9, v10, v11
	v_lshlrev_b32_e32 v10, 5, v4
	v_ashrrev_i16_sdwa v5, v224, sext(v5) dst_sel:DWORD dst_unused:UNUSED_PAD src0_sel:DWORD src1_sel:BYTE_0
	v_readlane_b32 s0, v247, 37
	v_and_b32_e32 v10, 32, v10
	v_bfe_i32 v5, v5, 0, 16
	v_readlane_b32 s1, v247, 38
	s_add_u32 s0, s40, s0
	v_add_lshl_u32 v7, v10, v5, 1
	s_addc_u32 s1, s41, s1
	s_add_i32 s25, s7, 0
	v_lshl_add_u32 v210, v9, 11, v7
	s_add_i32 m0, s25, 0x10000
	v_lshl_add_u32 v212, v8, 11, v7
	global_load_lds_dwordx4 v210, s[0:1]
	s_add_i32 m0, s25, 0x12000
	s_add_u32 s8, s0, 0x40000
	global_load_lds_dwordx4 v206, s[0:1]
	s_addc_u32 s9, s1, 0
	s_add_i32 m0, s25, 0x14000
	s_nop 0
	global_load_lds_dwordx4 v210, s[8:9]
	s_add_i32 m0, s25, 0x16000
	s_nop 0
	global_load_lds_dwordx4 v206, s[8:9]
	v_readlane_b32 s8, v247, 33
	v_readlane_b32 s9, v247, 34
	s_add_u32 s20, s54, s8
	s_addc_u32 s21, s55, s9
	s_add_i32 s27, s25, 0x2000
	s_mov_b32 m0, s25
	s_add_u32 s8, s20, 0x40000
	global_load_lds_dwordx4 v212, s[20:21]
	s_mov_b32 m0, s27
	s_addc_u32 s9, s21, 0
	s_add_i32 s29, s25, 0x4000
	global_load_lds_dwordx4 v208, s[20:21]
	s_mov_b32 m0, s29
	s_add_i32 s31, s25, 0x6000
	global_load_lds_dwordx4 v212, s[8:9]
	s_mov_b32 m0, s31
	s_cmp_eq_u32 s12, 1
	global_load_lds_dwordx4 v208, s[8:9]
	s_cselect_b64 s[8:9], -1, 0
	s_cmp_lg_u32 s12, 1
	s_cbranch_scc1 .LBB0_869
	s_barrier

; #define LAS __attribute__((address_space(3)))
; __device__ __forceinline__ SmallId small_id() { int tid = threadIdx.x; asm volatile("" : "+v"(tid)); SmallId i; i.w = __builtin_amdgcn_readfirstlane(tid >> 6); i.fr = tid & 15; i.fq = (tid & 63) >> 4; i.row = MP + 16 * i.w + i.fr; return i; }
; template <bool RES_F32, bool OUT_F32, int KSTEPS>
; __device__ __forceinline__ void small_res(const Params& p, LAS unsigned char* lds, const bf16_t* A, int lda, const bf16_t* Bt, int K, float* ssq_next, int G, int bx) {
;     const SmallId id = small_id();
;     bf16_t* XB = (bf16_t*)(p.ws + WS_XB);
;     for (int ts = G - 1 - bx; ts < DM / 32; ts += G) {
;         const int n0 = ts * 32; f32x4 acc[2] = {(f32x4){0.f, 0.f, 0.f, 0.f}, (f32x4){0.f, 0.f, 0.f, 0.f}};
; __global__ void __launch_bounds__(512) mk_fwd(Params p0) {
;     ...
;             if (l == 0) { small_res<true, false, 4>(p, lds, MIX, DM, (const bf16_t*)(wb + WO_OUT), DM, ssq + (2 * l + 1) * MPAD, G, bx);
.LBB0_903:
	s_and_b64 vcc, exec, s[0:1]
	s_cbranch_vccz .LBB0_947
	v_readlane_b32 s0, v246, 22
	s_add_u32 s2, s86, 0x20400
	v_mov_b32_e32 v0, v222
	v_readlane_b32 s1, v246, 23
	s_addc_u32 s3, s87, 0
	s_and_b64 vcc, exec, s[0:1]
	v_readfirstlane_b32 s0, v0
	s_ashr_i32 s7, s0, 6
	s_lshl_b32 s0, s7, 4
	v_and_b32_e32 v6, 15, v0
	s_add_i32 s0, s0, 0x8000
	v_or_b32_e32 v2, s0, v6
	v_bfe_u32 v7, v0, 4, 2
	s_lshl_b32 s0, s7, 7
	s_lshl_b32 s8, s7, 14
	v_lshlrev_b32_e32 v0, 4, v0
	s_lshl_b32 s7, s7, 11
	s_add_i32 s8, s8, 0
	v_and_b32_e32 v0, 0x3f0, v0
	s_add_i32 s7, s7, 0
	v_add_u32_e32 v78, s8, v0
	s_add_i32 s8, s7, 0x10400
	v_add_u32_e32 v81, s8, v0
	s_add_i32 s8, s7, 0x14400
	v_add_u32_e32 v83, s8, v0
	s_add_i32 s8, s7, 0x18400
	s_ashr_i32 s1, s0, 31
	v_add_u32_e32 v85, s8, v0
	v_readlane_b32 s8, v249, 4
	v_add_u32_e32 v79, s7, v0
	s_add_i32 s7, s7, 0x1c400
	v_ashrrev_i32_e32 v3, 31, v2
	v_readlane_b32 s9, v249, 5
	s_lshl_b64 s[0:1], s[0:1], 1
	v_add_u32_e32 v87, s7, v0
	s_waitcnt lgkmcnt(0)
	v_lshlrev_b64 v[0:1], 12, v[2:3]
	v_readlane_b32 s10, v249, 6
	v_readlane_b32 s11, v249, 7
	s_brev_b32 s8, 31
	s_add_u32 s0, s86, s0
	v_lshl_add_u64 v[0:1], s[10:11], 0, v[0:1]
	s_mov_b32 s9, -1
	s_addc_u32 s1, s87, s1
	s_mul_i32 s7, s93, 0x1b00000
	v_lshl_add_u64 v[68:69], v[0:1], 0, s[8:9]
	s_add_u32 s8, s0, s7
	v_lshlrev_b32_e32 v96, 4, v7
	s_addc_u32 s9, s1, 0
	v_lshlrev_b64 v[4:5], 11, v[2:3]
	v_lshl_add_u64 v[70:71], s[8:9], 0, v[96:97]
	v_readlane_b32 s7, v246, 8
	s_lshr_b32 s7, s7, 3
	s_lshl_b32 s7, s7, 5
	v_lshl_or_b32 v96, v6, 11, v96
	v_add_u32_e32 v80, 0x10000, v79
	v_add_u32_e32 v82, 0x14000, v79
	v_add_u32_e32 v84, 0x18000, v79
	v_add_u32_e32 v86, 0x1c000, v79
	v_lshlrev_b32_e32 v88, 2, v7
	v_lshl_add_u64 v[64:65], s[90:91], 0, v[4:5]
	v_cmp_eq_u32_e32 vcc, 0, v7
	v_lshl_add_u64 v[66:67], v[2:3], 2, s[2:3]
	v_add_u32_e32 v72, s7, v6
	v_lshl_add_u64 v[74:75], s[0:1], 0, v[96:97]
	v_readlane_b32 s7, v246, 8
	s_lshr_b32 s7, s7, 3
	v_readlane_b32 s12, v249, 8
	v_readlane_b32 s13, v249, 9
	v_readlane_b32 s14, v249, 10
	v_readlane_b32 s15, v249, 11
	v_readlane_b32 s16, v249, 12
	v_readlane_b32 s17, v249, 13
	v_readlane_b32 s18, v249, 14
	v_readlane_b32 s19, v249, 15
	v_readlane_b32 s20, v249, 16
	v_readlane_b32 s21, v249, 17
	v_readlane_b32 s22, v249, 18
	v_readlane_b32 s23, v249, 19
	s_branch .LBB0_907

; template <int KSTEPS  >
; __device__ __forceinline__ void small_mma_ksplit(f32x4 (&acc)[2], const bf16_t* A, int lda, const bf16_t* Bt, int ldb, int n0, LAS unsigned char* lds, const SmallId& id) {
;     const int lane = id.fq * 16 + id.fr, k0 = id.w * (KSTEPS * 32);
;     f32x4 part[8][2];
; #pragma unroll
;     for (int rb = 0; rb < 8; ++rb) { part[rb][0] = (f32x4){0.f, 0.f, 0.f, 0.f}; part[rb][1] = part[rb][0]; }
;     const bf16_t* ap = A + (size_t)(MP + id.fr) * lda + k0 + 8 * id.fq;
;     const bf16_t* bp = Bt + (size_t)(n0 + id.fr) * ldb + k0 + 8 * id.fq;
; #pragma unroll 1
;     for (int ks = 0; ks < KSTEPS; ++ks) {
;         bf16x8 a[8], b[2];
; #pragma unroll
;         for (int rb = 0; rb < 8; ++rb) a[rb] = *(const bf16x8*)(ap + (size_t)(16 * rb) * lda + 32 * ks);
;         b[0] = *(const bf16x8*)(bp + 32 * ks); b[1] = *(const bf16x8*)(bp + (size_t)16 * ldb + 32 * ks);
; #pragma unroll
;         for (int rb = 0; rb < 8; ++rb) { part[rb][0] = __builtin_amdgcn_mfma_f32_16x16x32_bf16(b[0], a[rb], part[rb][0], 0, 0, 0); part[rb][1] = __builtin_amdgcn_mfma_f32_16x16x32_bf16(b[1], a[rb], part[rb][1], 0, 0, 0); }
;     }
;     LAS f32x4* red = (LAS f32x4*)lds;
; #pragma unroll
;     for (int rb = 0; rb < 8; ++rb) { red[((id.w * 8 + rb) * 2 + 0) * 64 + lane] = part[rb][0]; red[((id.w * 8 + rb) * 2 + 1) * 64 + lane] = part[rb][1]; }
;     asm volatile("s_waitcnt lgkmcnt(0)" ::: "memory"); __syncthreads();
;     acc[0] = (f32x4){0.f, 0.f, 0.f, 0.f}; acc[1] = acc[0];
; #pragma unroll
;     for (int w2 = 0; w2 < 8; ++w2) { acc[0] += red[((w2 * 8 + id.w) * 2 + 0) * 64 + lane]; acc[1] += red[((w2 * 8 + id.w) * 2 + 1) * 64 + lane]; }
;     asm volatile("s_waitcnt lgkmcnt(0)" ::: "memory"); __syncthreads();
; template <bool RES_F32, bool OUT_F32, int KSTEPS>
; __device__ __forceinline__ void small_res(const Params& p, LAS unsigned char* lds, const bf16_t* A, int lda, const bf16_t* Bt, int K, float* ssq_next, int G, int bx) {
;     ...
;         float s = 0.f;
; #pragma unroll
;         for (int nb = 0; nb < 2; ++nb) { const int col = n0 + 16 * nb + 4 * id.fq;
;             f32x4 r;
;             if (RES_F32) r = *(const f32x4*)(p.xs + (size_t)(id.row - MP) * DM + col);
;             else { const u32x2 w = *(const u32x2*)(XB + (size_t)id.row * DM + col); r = (f32x4){bf_lo(w.x), bf_hi(w.x), bf_lo(w.y), bf_hi(w.y)}; }
;             const f32x4 x = r + acc[nb];
.LBB0_908:
	s_waitcnt lgkmcnt(0)
	v_readlane_b32 s8, v246, 8
	v_readfirstlane_b32 s32, v222
	s_and_b32 s8, s8, 7
	s_lshr_b32 s32, s32, 6
	s_cmp_eq_u32 s32, s8
	s_cselect_b32 s32, 1, 0
	s_lshl_b32 s9, s8, 11
	v_add_u32_e32 v70, s9, v78
	s_sub_i32 s9, s11, s10
	s_mul_i32 s8, s8, s9
	s_add_i32 s8, s8, s10
	s_mov_b32 s9, 0
	v_lshl_add_u64 v[72:73], v[74:75], 0, s[8:9]
	s_mov_b32 s8, s18
	v_lshl_add_u64 v[90:91], v[76:77], 0, s[8:9]
	s_mov_b32 s8, s19
	v_lshl_add_u64 v[92:93], v[76:77], 0, s[8:9]
	global_load_dwordx4 v[98:101], v[72:73], off
	global_load_dwordx4 v[102:105], v[90:91], off
	global_load_dwordx4 v[106:109], v[92:93], off
	global_load_dwordx4 v[110:113], v[72:73], off offset:64
	global_load_dwordx4 v[114:117], v[90:91], off offset:64
	global_load_dwordx4 v[118:121], v[92:93], off offset:64
	global_load_dwordx4 v[122:125], v[72:73], off offset:128
	global_load_dwordx4 v[126:129], v[90:91], off offset:128
	global_load_dwordx4 v[130:133], v[92:93], off offset:128
	global_load_dwordx4 v[134:137], v[72:73], off offset:192
	global_load_dwordx4 v[138:141], v[90:91], off offset:192
	global_load_dwordx4 v[142:145], v[92:93], off offset:192
	s_waitcnt vmcnt(9)
	v_mfma_f32_16x16x32_bf16 v[36:39], v[102:105], v[98:101], v[36:39]
	v_mfma_f32_16x16x32_bf16 v[24:27], v[106:109], v[98:101], v[24:27]
	s_waitcnt vmcnt(6)
	v_mfma_f32_16x16x32_bf16 v[36:39], v[114:117], v[110:113], v[36:39]
	v_mfma_f32_16x16x32_bf16 v[24:27], v[118:121], v[110:113], v[24:27]
	s_waitcnt vmcnt(3)
	v_mfma_f32_16x16x32_bf16 v[36:39], v[126:129], v[122:125], v[36:39]
	v_mfma_f32_16x16x32_bf16 v[24:27], v[130:133], v[122:125], v[24:27]
	s_waitcnt vmcnt(0)
	v_mfma_f32_16x16x32_bf16 v[36:39], v[138:141], v[134:137], v[36:39]
	v_mfma_f32_16x16x32_bf16 v[24:27], v[142:145], v[134:137], v[24:27]
	s_nop 7
	s_nop 1
	ds_write_b128 v70, v[36:39]
	ds_write_b128 v70, v[24:27] offset:1024
	s_waitcnt lgkmcnt(0)
	s_waitcnt lgkmcnt(0)
	s_barrier
	ds_read_b128 v[0:3], v79
	v_lshl_or_b32 v12, s7, 5, v88
	v_ashrrev_i32_e32 v13, 31, v12
	v_lshl_add_u64 v[14:15], v[12:13], 2, v[68:69]
	s_waitcnt lgkmcnt(0)
	v_pk_add_f32 v[4:5], v[2:3], 0 op_sel_hi:[1,0]
	v_pk_add_f32 v[6:7], v[0:1], 0 op_sel_hi:[1,0]
	ds_read_b128 v[0:3], v79 offset:1024
	s_waitcnt lgkmcnt(0)
	v_pk_add_f32 v[8:9], v[2:3], 0 op_sel_hi:[1,0]
	v_pk_add_f32 v[10:11], v[0:1], 0 op_sel_hi:[1,0]
	ds_read_b128 v[0:3], v79 offset:16384
	s_waitcnt lgkmcnt(0)
	v_pk_add_f32 v[4:5], v[4:5], v[2:3]
	v_pk_add_f32 v[6:7], v[6:7], v[0:1]
	ds_read_b128 v[0:3], v79 offset:17408
	s_waitcnt lgkmcnt(0)
	v_pk_add_f32 v[8:9], v[8:9], v[2:3]
	v_pk_add_f32 v[10:11], v[10:11], v[0:1]
	ds_read_b128 v[0:3], v79 offset:32768
	s_waitcnt lgkmcnt(0)
	v_pk_add_f32 v[4:5], v[4:5], v[2:3]
	v_pk_add_f32 v[6:7], v[6:7], v[0:1]
	ds_read_b128 v[0:3], v79 offset:33792
	s_waitcnt lgkmcnt(0)
	v_pk_add_f32 v[8:9], v[8:9], v[2:3]
	v_pk_add_f32 v[10:11], v[10:11], v[0:1]
	ds_read_b128 v[0:3], v79 offset:49152
	s_waitcnt lgkmcnt(0)
	v_pk_add_f32 v[4:5], v[4:5], v[2:3]
	v_pk_add_f32 v[6:7], v[6:7], v[0:1]
	ds_read_b128 v[0:3], v79 offset:50176
	s_waitcnt lgkmcnt(0)
	v_pk_add_f32 v[8:9], v[8:9], v[2:3]
	v_pk_add_f32 v[10:11], v[10:11], v[0:1]
	ds_read_b128 v[0:3], v80
	s_waitcnt lgkmcnt(0)
	v_pk_add_f32 v[4:5], v[4:5], v[2:3]
	v_pk_add_f32 v[6:7], v[6:7], v[0:1]
	ds_read_b128 v[0:3], v81
	s_waitcnt lgkmcnt(0)
	v_pk_add_f32 v[8:9], v[8:9], v[2:3]
	v_pk_add_f32 v[10:11], v[10:11], v[0:1]
	ds_read_b128 v[0:3], v82
	s_waitcnt lgkmcnt(0)
	v_pk_add_f32 v[4:5], v[4:5], v[2:3]
	v_pk_add_f32 v[6:7], v[6:7], v[0:1]
	ds_read_b128 v[0:3], v83
	s_waitcnt lgkmcnt(0)
	v_pk_add_f32 v[8:9], v[8:9], v[2:3]
	v_pk_add_f32 v[10:11], v[10:11], v[0:1]
	ds_read_b128 v[0:3], v84
	s_waitcnt lgkmcnt(0)
	v_pk_add_f32 v[4:5], v[4:5], v[2:3]
	v_pk_add_f32 v[6:7], v[6:7], v[0:1]
	ds_read_b128 v[0:3], v85
	s_waitcnt lgkmcnt(0)
	v_pk_add_f32 v[8:9], v[8:9], v[2:3]
	v_pk_add_f32 v[10:11], v[10:11], v[0:1]
	ds_read_b128 v[0:3], v86
	s_waitcnt lgkmcnt(0)
	v_pk_add_f32 v[4:5], v[4:5], v[2:3]
	v_pk_add_f32 v[6:7], v[6:7], v[0:1]
	ds_read_b128 v[0:3], v87
	s_waitcnt lgkmcnt(0)
	s_waitcnt lgkmcnt(0)
	s_barrier
	s_mul_i32 exec_lo, s32, -1
	s_mov_b32 exec_hi, exec_lo
	v_pk_add_f32 v[8:9], v[8:9], v[2:3]
	v_pk_add_f32 v[10:11], v[10:11], v[0:1]
	global_load_dwordx4 v[0:3], v[14:15], off
	s_waitcnt vmcnt(0)
	v_pk_add_f32 v[0:1], v[6:7], v[0:1]
	v_pk_add_f32 v[2:3], v[4:5], v[2:3]
	v_cvt_pk_bf16_f32 v4, v0, v1
	v_mul_f32_e32 v1, v1, v1
	v_lshl_add_u64 v[6:7], v[12:13], 1, v[64:65]
	v_fmac_f32_e32 v1, v0, v0
	v_mul_f32_e32 v0, v3, v3
	v_cvt_pk_bf16_f32 v5, v2, v3
	global_store_dwordx2 v[6:7], v[4:5], off
	v_fmac_f32_e32 v0, v2, v2
	v_add_f32_e32 v12, v1, v0
	global_load_dwordx4 v[0:3], v[14:15], off offset:64
	s_waitcnt vmcnt(0)
	v_pk_add_f32 v[0:1], v[10:11], v[0:1]
	v_pk_add_f32 v[2:3], v[8:9], v[2:3]
	v_cvt_pk_bf16_f32 v4, v0, v1
	v_mul_f32_e32 v1, v1, v1
	v_fmac_f32_e32 v1, v0, v0
	v_mul_f32_e32 v0, v3, v3
	v_cvt_pk_bf16_f32 v5, v2, v3
	v_fmac_f32_e32 v0, v2, v2
	v_and_b32_e32 v2, 64, v225
	v_add_f32_e32 v0, v1, v0
	v_xor_b32_e32 v1, 16, v225
	v_add_u32_e32 v2, 64, v2
	v_cmp_lt_i32_e64 s[0:1], v1, v2
	v_add_f32_e32 v0, v12, v0
	global_store_dwordx2 v[6:7], v[4:5], off offset:32
	v_cndmask_b32_e64 v1, v225, v1, s[0:1]
	v_lshlrev_b32_e32 v1, 2, v1
	ds_bpermute_b32 v1, v1, v0
	s_waitcnt lgkmcnt(0)
	v_add_f32_e32 v0, v0, v1
	v_xor_b32_e32 v1, 32, v225
	v_cmp_lt_i32_e64 s[0:1], v1, v2
	s_nop 1
	v_cndmask_b32_e64 v1, v225, v1, s[0:1]
	v_lshlrev_b32_e32 v1, 2, v1
	ds_bpermute_b32 v1, v1, v0
	s_and_saveexec_b64 s[0:1], vcc
	s_cbranch_execz .LBB0_906
	s_waitcnt lgkmcnt(0)
	v_add_f32_e32 v0, v0, v1
	global_atomic_add_f32 v[66:67], v0, off
	s_branch .LBB0_906
; #define PG8_STAGE(bufoff, gbase, voff) do { _Pragma("unroll") for (int _i = 0; _i < 2; ++_i) \
;         __builtin_amdgcn_global_load_lds((const unsigned*)((const char*)(gbase) + (voff)[_i]), (LAS unsigned*)(lds + (bufoff) + ldsw + _i * 8192), 16, 0, 0); } while (0)
; #define PG8_BAR __builtin_amdgcn_s_barrier()
;     __device__ __forceinline__ bool next(int i, Unit& u) const { u.z = 0; return o.tile(i, u); }
;     __device__ __forceinline__ long a_off(const Unit& u) const { return (long)u.pm * tA; }
;     __device__ __forceinline__ long b_off(const Unit& u) const { return (long)u.pn * tB; }
;     __device__ __forceinline__ bool next(int i, Unit& u) const { u.z = i & 1; return o.tile(i >> 1, u); }
; template <class Epi, class Sched>
; __device__ __forceinline__ void gemm_phase(LAS unsigned char* lds, const Gemm g, const Sched& S, const Epi& E) {
;     ...
;     const int wid = __builtin_amdgcn_readfirstlane(tid >> 6), lane = tid & 63, wr = wid >> 2, wc = wid & 3, fr = lane & 15, fq = lane >> 4;
;     const int K = g.K, nt = K / BK;
;     unsigned voffA[2], voffB[2];
; #pragma unroll
;     for (int i = 0; i < 2; ++i) { int R, C; stage_rc(tid * 16 + i * 8192, R, C); const int Rb = Epi::PERM ? ((R & ~31) + perm32(R & 31)) : R;
;         voffA[i] = (unsigned)(R * g.lda + C) * 2u; voffB[i] = (unsigned)(Rb * g.ldb + C) * 2u; }
;     const size_t kstep = (size_t)(BK * 2);
;     const size_t hstepA = (size_t)HALF * g.lda * 2, hstepB = (size_t)HALF * g.ldb * 2;
;     const unsigned ldsw = (unsigned)wid * 1024u;
;     const int aoff = lds_byte(wr * 64 + fr, fq * 8), boff = lds_byte(wc * 32 + fr, fq * 8);
;     ...
;     Unit cur, nxt; int ui = 0;
;     if (!S.next(0, cur)) return;
;     f32x4 acc[2][2][4][2];
; #pragma unroll
;     for (int a = 0; a < 2; ++a)
; #pragma unroll
;         for (int b = 0; b < 2; ++b)
; #pragma unroll
;             for (int m = 0; m < 4; ++m)
; #pragma unroll
;                 for (int n = 0; n < 2; ++n) acc[a][b][m][n] = (f32x4){0.f, 0.f, 0.f, 0.f};
;     bf16x8 At[4][2], B0[2][2], B1[2][2];
;     const char* cA = (const char*)g.A + S.a_off(cur); const char* cB = (const char*)g.Bt + S.b_off(cur);
;     PG8_STAGE(PG8_SB(0, 0), cB, voffB); PG8_STAGE(PG8_SB(0, 1), cB + hstepB, voffB); PG8_STAGE(PG8_SA(0, 0), cA, voffA); PG8_STAGE(PG8_SA(0, 1), cA + hstepA, voffA);
;     if (wr == 1) PG8_BAR;
.LBB0_911:
	s_mov_b64 exec, -1
	v_readlane_b32 s0, v246, 24
	v_mov_b32_e32 v6, v222
	v_readlane_b32 s1, v246, 25
	s_and_b64 vcc, exec, s[0:1]
	v_readfirstlane_b32 s10, v6
	s_cbranch_vccnz .LBB0_947
	v_lshlrev_b32_e32 v3, 4, v6
	s_waitcnt lgkmcnt(0)
	v_add_u32_e32 v1, 0x2000, v3
	v_ashrrev_i32_e32 v0, 31, v1
	v_lshrrev_b32_e32 v0, 22, v0
	v_add_u32_e32 v0, v1, v0
	v_ashrrev_i32_e32 v0, 10, v0
	v_mul_i32_i24_e32 v2, 0x400, v0
	v_sub_u32_e32 v1, v1, v2
	v_lshrrev_b32_e32 v2, 4, v1
	v_bitop3_b32 v2, v2, v1, 32 bitop3:0x6c
	v_ashrrev_i32_e32 v1, 31, v2
	v_lshrrev_b32_e32 v1, 26, v1
	v_add_u32_e32 v4, v2, v1
	v_lshlrev_b32_e32 v5, 3, v0
	v_ashrrev_i32_e32 v1, 6, v4
	v_and_b32_e32 v5, -16, v5
	v_add_u32_e32 v5, v1, v5
	v_and_b32_e32 v7, 3, v1
	s_mov_b32 s0, 0x1fffe0
	v_lshrrev_b32_e32 v8, 2, v5
	v_lshlrev_b32_e32 v9, 1, v5
	v_and_b32_e32 v4, 0xc0, v4
	v_and_or_b32 v7, v5, s0, v7
	v_and_b32_e32 v8, 4, v8
	v_and_b32_e32 v9, 24, v9
	v_sub_u32_e32 v2, v2, v4
	v_or3_b32 v7, v7, v8, v9
	v_lshlrev_b32_e32 v8, 5, v0
	v_ashrrev_i16_sdwa v2, v224, sext(v2) dst_sel:DWORD dst_unused:UNUSED_PAD src0_sel:DWORD src1_sel:BYTE_0
	v_and_b32_e32 v8, 32, v8
	v_bfe_i32 v2, v2, 0, 16
	v_add_lshl_u32 v4, v8, v2, 1
	v_lshl_add_u32 v178, v7, 11, v4
	v_lshl_add_u32 v180, v5, 11, v4
	v_bfe_i32 v4, v6, 27, 1
	v_lshrrev_b32_e32 v4, 22, v4
	v_add_u32_e32 v4, v3, v4
	v_and_b32_e32 v4, 0xfffffc00, v4
	v_sub_u32_e32 v3, v3, v4
	v_lshrrev_b32_e32 v4, 4, v3
	v_bitop3_b32 v5, v4, v3, 32 bitop3:0x6c
	v_ashrrev_i32_e32 v4, 31, v6
	v_lshrrev_b32_e32 v4, 26, v4
	v_ashrrev_i32_e32 v3, 31, v5
	v_add_u32_e32 v4, v6, v4
	v_lshrrev_b32_e32 v3, 26, v3
	v_ashrrev_i32_e32 v4, 6, v4
	v_add_u32_e32 v7, v5, v3
	v_lshlrev_b32_e32 v8, 3, v4
	v_ashrrev_i32_e32 v3, 6, v7
	v_and_b32_e32 v8, -16, v8
	v_add_u32_e32 v8, v3, v8
	v_and_b32_e32 v9, 3, v3
	v_lshrrev_b32_e32 v10, 2, v8
	v_lshlrev_b32_e32 v11, 1, v8
	v_and_b32_e32 v7, 0xc0, v7
	s_ashr_i32 s11, s10, 6
	v_and_or_b32 v9, v8, s0, v9
	v_and_b32_e32 v10, 4, v10
	v_and_b32_e32 v11, 24, v11
	v_sub_u32_e32 v5, v5, v7
	s_ashr_i32 s12, s10, 8
	s_lshl_b32 s7, s11, 10
	v_or3_b32 v9, v9, v10, v11
	v_lshlrev_b32_e32 v10, 5, v4
	v_ashrrev_i16_sdwa v5, v224, sext(v5) dst_sel:DWORD dst_unused:UNUSED_PAD src0_sel:DWORD src1_sel:BYTE_0
	v_readlane_b32 s0, v247, 37
	v_and_b32_e32 v10, 32, v10
	v_bfe_i32 v5, v5, 0, 16
	v_readlane_b32 s1, v247, 38
	s_add_u32 s0, s40, s0
	v_add_lshl_u32 v7, v10, v5, 1
	s_addc_u32 s1, s41, s1
	s_add_i32 s25, s7, 0
	v_lshl_add_u32 v96, v9, 11, v7
	s_add_i32 m0, s25, 0x10000
	v_lshl_add_u32 v182, v8, 11, v7
	global_load_lds_dwordx4 v96, s[0:1]
	s_add_i32 m0, s25, 0x12000
	s_add_u32 s8, s0, 0x40000
	global_load_lds_dwordx4 v178, s[0:1]
	s_addc_u32 s9, s1, 0
	s_add_i32 m0, s25, 0x14000
	s_nop 0
	global_load_lds_dwordx4 v96, s[8:9]
	s_add_i32 m0, s25, 0x16000
	s_nop 0
	global_load_lds_dwordx4 v178, s[8:9]
	v_readlane_b32 s8, v247, 33
	v_readlane_b32 s9, v247, 34
	s_add_u32 s20, s54, s8
	s_addc_u32 s21, s55, s9
	s_add_i32 s27, s25, 0x2000
	s_mov_b32 m0, s25
	s_add_u32 s8, s20, 0x40000
	global_load_lds_dwordx4 v182, s[20:21]
	s_mov_b32 m0, s27
	s_addc_u32 s9, s21, 0
	s_add_i32 s29, s25, 0x4000
	global_load_lds_dwordx4 v180, s[20:21]
	s_mov_b32 m0, s29
	s_add_i32 s31, s25, 0x6000
	global_load_lds_dwordx4 v182, s[8:9]
	s_mov_b32 m0, s31
	s_cmp_eq_u32 s12, 1
	global_load_lds_dwordx4 v180, s[8:9]
	s_cselect_b64 s[8:9], -1, 0
	s_cmp_lg_u32 s12, 1
	s_cbranch_scc1 .LBB0_914
	s_barrier

; #define LAS __attribute__((address_space(3)))
; __device__ __forceinline__ SmallId small_id() { int tid = threadIdx.x; asm volatile("" : "+v"(tid)); SmallId i; i.w = __builtin_amdgcn_readfirstlane(tid >> 6); i.fr = tid & 15; i.fq = (tid & 63) >> 4; i.row = MP + 16 * i.w + i.fr; return i; }
; template <bool RES_F32, bool OUT_F32, int KSTEPS>
; __device__ __forceinline__ void small_res(const Params& p, LAS unsigned char* lds, const bf16_t* A, int lda, const bf16_t* Bt, int K, float* ssq_next, int G, int bx) {
;     const SmallId id = small_id();
;     bf16_t* XB = (bf16_t*)(p.ws + WS_XB);
;     for (int ts = G - 1 - bx; ts < DM / 32; ts += G) {
;         const int n0 = ts * 32; f32x4 acc[2] = {(f32x4){0.f, 0.f, 0.f, 0.f}, (f32x4){0.f, 0.f, 0.f, 0.f}};
; __global__ void __launch_bounds__(512) mk_fwd(Params p0) {
;     ...
;               asm volatile("s_waitcnt vmcnt(0)" ::: "memory"); __syncthreads(); }
;             for (int rep = 0; rep < DRY_P6; ++rep) { EpiNone E0{ssq}; pg8::gemm_phase(lds, g, S, E0); }
;             if (l == 0) { small_res<false, false, 11>(p, lds, U, FF, (const bf16_t*)(wb + WO_DOWN), FF, ssq + 2 * MPAD, G, bx);
;                           EpiRes<false, false> E{p.xp, p.out, XB, ssq + 2 * MPAD}; pg8::gemm_phase(lds, g, S, E); }
;             else        { small_res<false, true, 11>(p, lds, U, FF, (const bf16_t*)(wb + WO_DOWN), FF, nullptr, G, bx);
.LBB0_1219:
	v_readlane_b32 s0, v246, 16
	s_waitcnt vmcnt(0)
	v_readlane_b32 s2, v246, 13
	s_add_u32 s22, s0, 0x1580000
	v_readlane_b32 s0, v246, 17
	v_readlane_b32 s3, v246, 14
	v_readlane_b32 s54, v248, 44
	s_addc_u32 s23, s0, 0
	s_mov_b64 s[0:1], -1
	s_and_b64 vcc, exec, s[2:3]
	v_readlane_b32 s81, v246, 8
	v_readlane_b32 s92, v246, 9
	v_readlane_b32 s55, v248, 45
	s_mov_b32 s52, 0x1ab00000
	s_mov_b32 s53, 0x1ab16000
	s_mov_b32 s56, 0x1ab2c000
	s_mov_b32 s57, 0x1ab42000
	s_mov_b32 s58, 0x1ab58000
	s_mov_b32 s59, 0x1ab6e000
	s_mov_b32 s60, 0x1ab84000
	s_mov_b32 s61, 0x1ab9a000
	s_mov_b32 s62, 0x1680000
	s_mov_b32 s63, 0x1696000
	s_waitcnt lgkmcnt(0)
	s_barrier
	v_readlane_b32 s93, v246, 10
	s_cbranch_vccz .LBB0_1250
	v_readlane_b32 s0, v246, 22
	v_mov_b32_e32 v0, v222
	v_readlane_b32 s1, v246, 23
	v_readlane_b32 s64, v246, 11
	s_and_b64 vcc, exec, s[0:1]
	v_readfirstlane_b32 s0, v0
	v_readlane_b32 s65, v246, 12
	s_ashr_i32 s2, s0, 6
	s_lshl_b32 s0, s2, 4
	v_and_b32_e32 v4, 15, v0
	s_add_i32 s0, s0, 0x8000
	v_or_b32_e32 v2, s0, v4
	v_bfe_u32 v5, v0, 4, 2
	s_mul_i32 s0, s2, 0x160
	s_lshl_b32 s3, s2, 14
	v_lshlrev_b32_e32 v0, 4, v0
	s_lshl_b32 s2, s2, 11
	s_add_i32 s3, s3, 0
	v_and_b32_e32 v0, 0x3f0, v0
	s_add_i32 s2, s2, 0
	v_add_u32_e32 v74, s3, v0
	s_add_i32 s3, s2, 0x10400
	s_ashr_i32 s1, s0, 31
	v_add_u32_e32 v77, s3, v0
	s_add_i32 s3, s2, 0x14400
	v_add_u32_e32 v75, s2, v0
	v_add_u32_e32 v79, s3, v0
	s_add_i32 s3, s2, 0x18400
	s_add_i32 s2, s2, 0x1c400
	s_lshl_b64 s[0:1], s[0:1], 1
	v_add_u32_e32 v83, s2, v0
	v_ashrrev_i32_e32 v3, 31, v2
	s_add_u32 s2, s86, s0
	v_add_u32_e32 v81, s3, v0
	v_lshlrev_b64 v[0:1], 11, v[2:3]
	s_addc_u32 s3, s87, s1
	v_readlane_b32 s7, v246, 15
	v_lshl_add_u64 v[64:65], s[90:91], 0, v[0:1]
	v_lshlrev_b64 v[0:1], 12, v[2:3]
	s_add_u32 s2, s2, s7
	v_lshl_add_u64 v[66:67], s[64:65], 0, v[0:1]
	v_lshlrev_b32_e32 v0, 4, v5
	v_mov_b32_e32 v1, v97
	s_addc_u32 s3, s3, 0
	v_mul_u32_u24_e32 v96, 0x1600, v4
	v_lshl_add_u64 v[68:69], s[2:3], 0, v[0:1]
	v_or_b32_e32 v0, s0, v0
	v_mov_b32_e32 v1, s1
	v_readlane_b32 s2, v246, 8
	s_lshr_b32 s2, s2, 3
	s_lshl_b32 s2, s2, 5
	v_lshl_add_u64 v[0:1], v[0:1], 0, v[96:97]
	v_add_u32_e32 v76, 0x10000, v75
	v_add_u32_e32 v78, 0x14000, v75
	v_add_u32_e32 v80, 0x18000, v75
	v_add_u32_e32 v82, 0x1c000, v75
	v_lshlrev_b32_e32 v84, 2, v5
	v_add_u32_e32 v85, s2, v4
	v_lshl_add_u64 v[70:71], s[86:87], 0, v[0:1]
	v_readlane_b32 s2, v246, 8
	s_lshr_b32 s2, s2, 3

; #define LAS __attribute__((address_space(3)))
; template <int KSTEPS  >
; __device__ __forceinline__ void small_mma_ksplit(f32x4 (&acc)[2], const bf16_t* A, int lda, const bf16_t* Bt, int ldb, int n0, LAS unsigned char* lds, const SmallId& id) {
;     const int lane = id.fq * 16 + id.fr, k0 = id.w * (KSTEPS * 32);
;     f32x4 part[8][2];
; #pragma unroll
;     for (int rb = 0; rb < 8; ++rb) { part[rb][0] = (f32x4){0.f, 0.f, 0.f, 0.f}; part[rb][1] = part[rb][0]; }
;     const bf16_t* ap = A + (size_t)(MP + id.fr) * lda + k0 + 8 * id.fq;
;     const bf16_t* bp = Bt + (size_t)(n0 + id.fr) * ldb + k0 + 8 * id.fq;
; #pragma unroll 1
;     for (int ks = 0; ks < KSTEPS; ++ks) {
;         bf16x8 a[8], b[2];
; #pragma unroll
;         for (int rb = 0; rb < 8; ++rb) a[rb] = *(const bf16x8*)(ap + (size_t)(16 * rb) * lda + 32 * ks);
;         b[0] = *(const bf16x8*)(bp + 32 * ks); b[1] = *(const bf16x8*)(bp + (size_t)16 * ldb + 32 * ks);
; #pragma unroll
;         for (int rb = 0; rb < 8; ++rb) { part[rb][0] = __builtin_amdgcn_mfma_f32_16x16x32_bf16(b[0], a[rb], part[rb][0], 0, 0, 0); part[rb][1] = __builtin_amdgcn_mfma_f32_16x16x32_bf16(b[1], a[rb], part[rb][1], 0, 0, 0); }
;     }
;     LAS f32x4* red = (LAS f32x4*)lds;
; #pragma unroll
;     for (int rb = 0; rb < 8; ++rb) { red[((id.w * 8 + rb) * 2 + 0) * 64 + lane] = part[rb][0]; red[((id.w * 8 + rb) * 2 + 1) * 64 + lane] = part[rb][1]; }
;     asm volatile("s_waitcnt lgkmcnt(0)" ::: "memory"); __syncthreads();
;     acc[0] = (f32x4){0.f, 0.f, 0.f, 0.f}; acc[1] = acc[0];
; #pragma unroll
;     for (int w2 = 0; w2 < 8; ++w2) { acc[0] += red[((w2 * 8 + id.w) * 2 + 0) * 64 + lane]; acc[1] += red[((w2 * 8 + id.w) * 2 + 1) * 64 + lane]; }
;     asm volatile("s_waitcnt lgkmcnt(0)" ::: "memory"); __syncthreads();
.LBB0_1223:
	s_waitcnt lgkmcnt(0)
	v_readlane_b32 s0, v246, 8
	v_readfirstlane_b32 s32, v222
	s_and_b32 s0, s0, 7
	s_lshr_b32 s32, s32, 6
	s_cmp_eq_u32 s32, s0
	s_cselect_b32 s32, 1, 0
	s_lshl_b32 s1, s0, 11
	v_add_u32_e32 v68, s1, v74
	s_sub_i32 s1, s53, s52
	s_mul_i32 s0, s0, s1
	s_add_i32 s0, s0, s52
	s_mov_b32 s1, 0
	v_lshl_add_u64 v[86:87], v[70:71], 0, s[0:1]
	s_mov_b32 s0, s62
	v_lshl_add_u64 v[88:89], v[72:73], 0, s[0:1]
	s_mov_b32 s0, s63
	v_lshl_add_u64 v[90:91], v[72:73], 0, s[0:1]
	global_load_dwordx4 v[92:95], v[86:87], off
	global_load_dwordx4 v[98:101], v[88:89], off
	global_load_dwordx4 v[102:105], v[90:91], off
	global_load_dwordx4 v[106:109], v[86:87], off offset:64
	global_load_dwordx4 v[110:113], v[88:89], off offset:64
	global_load_dwordx4 v[114:117], v[90:91], off offset:64
	global_load_dwordx4 v[118:121], v[86:87], off offset:128
	global_load_dwordx4 v[122:125], v[88:89], off offset:128
	global_load_dwordx4 v[126:129], v[90:91], off offset:128
	global_load_dwordx4 v[130:133], v[86:87], off offset:192
	global_load_dwordx4 v[134:137], v[88:89], off offset:192
	global_load_dwordx4 v[138:141], v[90:91], off offset:192
	global_load_dwordx4 v[142:145], v[86:87], off offset:256
	global_load_dwordx4 v[146:149], v[88:89], off offset:256
	global_load_dwordx4 v[150:153], v[90:91], off offset:256
	global_load_dwordx4 v[154:157], v[86:87], off offset:320
	global_load_dwordx4 v[158:161], v[88:89], off offset:320
	global_load_dwordx4 v[162:165], v[90:91], off offset:320
	global_load_dwordx4 v[166:169], v[86:87], off offset:384
	global_load_dwordx4 v[170:173], v[88:89], off offset:384
	global_load_dwordx4 v[174:177], v[90:91], off offset:384
	global_load_dwordx4 v[178:181], v[86:87], off offset:448
	global_load_dwordx4 v[182:185], v[88:89], off offset:448
	global_load_dwordx4 v[186:189], v[90:91], off offset:448
	s_waitcnt vmcnt(21)
	v_mfma_f32_16x16x32_bf16 v[36:39], v[98:101], v[92:95], v[36:39]
	v_mfma_f32_16x16x32_bf16 v[24:27], v[102:105], v[92:95], v[24:27]
	global_load_dwordx4 v[92:95], v[86:87], off offset:512
	global_load_dwordx4 v[98:101], v[88:89], off offset:512
	global_load_dwordx4 v[102:105], v[90:91], off offset:512
	s_waitcnt vmcnt(21)
	v_mfma_f32_16x16x32_bf16 v[36:39], v[110:113], v[106:109], v[36:39]
	v_mfma_f32_16x16x32_bf16 v[24:27], v[114:117], v[106:109], v[24:27]
	global_load_dwordx4 v[106:109], v[86:87], off offset:576
	global_load_dwordx4 v[110:113], v[88:89], off offset:576
	global_load_dwordx4 v[114:117], v[90:91], off offset:576
	s_waitcnt vmcnt(21)
	v_mfma_f32_16x16x32_bf16 v[36:39], v[122:125], v[118:121], v[36:39]
	v_mfma_f32_16x16x32_bf16 v[24:27], v[126:129], v[118:121], v[24:27]
	global_load_dwordx4 v[118:121], v[86:87], off offset:640
	global_load_dwordx4 v[122:125], v[88:89], off offset:640
	global_load_dwordx4 v[126:129], v[90:91], off offset:640
	s_waitcnt vmcnt(21)
	v_mfma_f32_16x16x32_bf16 v[36:39], v[134:137], v[130:133], v[36:39]
	v_mfma_f32_16x16x32_bf16 v[24:27], v[138:141], v[130:133], v[24:27]
	s_waitcnt vmcnt(18)
	v_mfma_f32_16x16x32_bf16 v[36:39], v[146:149], v[142:145], v[36:39]
	v_mfma_f32_16x16x32_bf16 v[24:27], v[150:153], v[142:145], v[24:27]
	s_waitcnt vmcnt(15)
	v_mfma_f32_16x16x32_bf16 v[36:39], v[158:161], v[154:157], v[36:39]
	v_mfma_f32_16x16x32_bf16 v[24:27], v[162:165], v[154:157], v[24:27]
	s_waitcnt vmcnt(12)
	v_mfma_f32_16x16x32_bf16 v[36:39], v[170:173], v[166:169], v[36:39]
	v_mfma_f32_16x16x32_bf16 v[24:27], v[174:177], v[166:169], v[24:27]
	s_waitcnt vmcnt(9)
	v_mfma_f32_16x16x32_bf16 v[36:39], v[182:185], v[178:181], v[36:39]
	v_mfma_f32_16x16x32_bf16 v[24:27], v[186:189], v[178:181], v[24:27]
	s_waitcnt vmcnt(6)
	v_mfma_f32_16x16x32_bf16 v[36:39], v[98:101], v[92:95], v[36:39]
	v_mfma_f32_16x16x32_bf16 v[24:27], v[102:105], v[92:95], v[24:27]
	s_waitcnt vmcnt(3)
	v_mfma_f32_16x16x32_bf16 v[36:39], v[110:113], v[106:109], v[36:39]
	v_mfma_f32_16x16x32_bf16 v[24:27], v[114:117], v[106:109], v[24:27]
	s_waitcnt vmcnt(0)
	v_mfma_f32_16x16x32_bf16 v[36:39], v[122:125], v[118:121], v[36:39]
	v_mfma_f32_16x16x32_bf16 v[24:27], v[126:129], v[118:121], v[24:27]
	s_nop 7
	s_nop 1
	ds_write_b128 v68, v[36:39]
	ds_write_b128 v68, v[24:27] offset:1024
	s_waitcnt lgkmcnt(0)
	s_waitcnt lgkmcnt(0)
	s_barrier
	ds_read_b128 v[0:3], v75
	v_lshl_or_b32 v12, s2, 5, v84
	v_ashrrev_i32_e32 v13, 31, v12
	v_lshl_add_u64 v[14:15], v[12:13], 1, v[64:65]
	s_add_i32 s2, s2, s92
	s_waitcnt lgkmcnt(0)
	v_pk_add_f32 v[4:5], v[2:3], 0 op_sel_hi:[1,0]
	v_pk_add_f32 v[6:7], v[0:1], 0 op_sel_hi:[1,0]
	ds_read_b128 v[0:3], v75 offset:1024
	v_add_u32_e32 v85, s37, v85
	s_cmp_lt_i32 s2, 32
	s_waitcnt lgkmcnt(0)
	v_pk_add_f32 v[8:9], v[2:3], 0 op_sel_hi:[1,0]
	v_pk_add_f32 v[10:11], v[0:1], 0 op_sel_hi:[1,0]
	ds_read_b128 v[0:3], v75 offset:16384
	s_waitcnt lgkmcnt(0)
	v_pk_add_f32 v[4:5], v[4:5], v[2:3]
	v_pk_add_f32 v[6:7], v[6:7], v[0:1]
	ds_read_b128 v[0:3], v75 offset:17408
	s_waitcnt lgkmcnt(0)
	v_pk_add_f32 v[8:9], v[8:9], v[2:3]
	v_pk_add_f32 v[10:11], v[10:11], v[0:1]
	ds_read_b128 v[0:3], v75 offset:32768
	s_waitcnt lgkmcnt(0)
	v_pk_add_f32 v[4:5], v[4:5], v[2:3]
	v_pk_add_f32 v[6:7], v[6:7], v[0:1]
	ds_read_b128 v[0:3], v75 offset:33792
	s_waitcnt lgkmcnt(0)
	v_pk_add_f32 v[8:9], v[8:9], v[2:3]
	v_pk_add_f32 v[10:11], v[10:11], v[0:1]
	ds_read_b128 v[0:3], v75 offset:49152
	s_waitcnt lgkmcnt(0)
	v_pk_add_f32 v[4:5], v[4:5], v[2:3]
	v_pk_add_f32 v[6:7], v[6:7], v[0:1]
	ds_read_b128 v[0:3], v75 offset:50176
	s_waitcnt lgkmcnt(0)
	v_pk_add_f32 v[8:9], v[8:9], v[2:3]
	v_pk_add_f32 v[10:11], v[10:11], v[0:1]
	ds_read_b128 v[0:3], v76
	s_waitcnt lgkmcnt(0)
	v_pk_add_f32 v[4:5], v[4:5], v[2:3]
	v_pk_add_f32 v[6:7], v[6:7], v[0:1]
	ds_read_b128 v[0:3], v77
	s_waitcnt lgkmcnt(0)
	v_pk_add_f32 v[8:9], v[8:9], v[2:3]
	v_pk_add_f32 v[10:11], v[10:11], v[0:1]
	ds_read_b128 v[0:3], v78
	s_waitcnt lgkmcnt(0)
	v_pk_add_f32 v[4:5], v[4:5], v[2:3]
	v_pk_add_f32 v[6:7], v[6:7], v[0:1]
	ds_read_b128 v[0:3], v79
	s_waitcnt lgkmcnt(0)
	v_pk_add_f32 v[8:9], v[8:9], v[2:3]
	v_pk_add_f32 v[10:11], v[10:11], v[0:1]
	ds_read_b128 v[0:3], v80
	s_waitcnt lgkmcnt(0)
	v_pk_add_f32 v[4:5], v[4:5], v[2:3]
	v_pk_add_f32 v[6:7], v[6:7], v[0:1]
	ds_read_b128 v[0:3], v81
	s_waitcnt lgkmcnt(0)
	v_pk_add_f32 v[8:9], v[8:9], v[2:3]
	v_pk_add_f32 v[10:11], v[10:11], v[0:1]
	ds_read_b128 v[0:3], v82
	s_waitcnt lgkmcnt(0)
	v_pk_add_f32 v[4:5], v[4:5], v[2:3]
	v_pk_add_f32 v[6:7], v[6:7], v[0:1]
	ds_read_b128 v[0:3], v83
	s_waitcnt lgkmcnt(0)
	s_waitcnt lgkmcnt(0)
	s_barrier
;     __device__ __forceinline__ bool next(int i, Unit& u) const { u.z = 0; return o.tile(i, u); }
; template <class Epi, class Sched>
; __device__ __forceinline__ void gemm_phase(LAS unsigned char* lds, const Gemm g, const Sched& S, const Epi& E) {
;     ...
;     for (int i = 0; i < 2; ++i) { int R, C; stage_rc(tid * 16 + i * 8192, R, C); const int Rb = Epi::PERM ? ((R & ~31) + perm32(R & 31)) : R;
;         voffA[i] = (unsigned)(R * g.lda + C) * 2u; voffB[i] = (unsigned)(Rb * g.ldb + C) * 2u; }
;     const size_t kstep = (size_t)(BK * 2);
;     const size_t hstepA = (size_t)HALF * g.lda * 2, hstepB = (size_t)HALF * g.ldb * 2;
;     const unsigned ldsw = (unsigned)wid * 1024u;
;     const int aoff = lds_byte(wr * 64 + fr, fq * 8), boff = lds_byte(wc * 32 + fr, fq * 8);
;     ...
;     Unit cur, nxt; int ui = 0;
;     if (!S.next(0, cur)) return;
;     f32x4 acc[2][2][4][2];
; #pragma unroll
;     for (int a = 0; a < 2; ++a)
; #pragma unroll
;         for (int b = 0; b < 2; ++b)
; #pragma unroll
;             for (int m = 0; m < 4; ++m)
; #pragma unroll
;                 for (int n = 0; n < 2; ++n) acc[a][b][m][n] = (f32x4){0.f, 0.f, 0.f, 0.f};
;     bf16x8 At[4][2], B0[2][2], B1[2][2];
;     const char* cA = (const char*)g.A + S.a_off(cur); const char* cB = (const char*)g.Bt + S.b_off(cur);
; template <bool RES_F32, bool OUT_F32, int KSTEPS>
; __device__ __forceinline__ void small_res(const Params& p, LAS unsigned char* lds, const bf16_t* A, int lda, const bf16_t* Bt, int K, float* ssq_next, int G, int bx) {
;     ...
;         float s = 0.f;
; #pragma unroll
;         for (int nb = 0; nb < 2; ++nb) { const int col = n0 + 16 * nb + 4 * id.fq;
;             f32x4 r;
;             if (RES_F32) r = *(const f32x4*)(p.xs + (size_t)(id.row - MP) * DM + col);
;             else { const u32x2 w = *(const u32x2*)(XB + (size_t)id.row * DM + col); r = (f32x4){bf_lo(w.x), bf_hi(w.x), bf_lo(w.y), bf_hi(w.y)}; }
;             const f32x4 x = r + acc[nb];
;             if (OUT_F32) *(f32x4*)(p.out + (size_t)id.row * DM + col) = x;
;             else { u32x2 w; w.x = cvt_pk_bf16(x[0], x[1]); w.y = cvt_pk_bf16(x[2], x[3]); *(u32x2*)(XB + (size_t)id.row * DM + col) = w; }
;             s += (x[0] * x[0] + x[1] * x[1]) + (x[2] * x[2] + x[3] * x[3]); }
;         if (!OUT_F32) { s += __shfl_xor(s, 16); s += __shfl_xor(s, 32); if (id.fq == 0) atomicAdd(ssq_next + id.row, s); }
;     }
	s_mul_i32 exec_lo, s32, -1
	s_mov_b32 exec_hi, exec_lo
	v_pk_add_f32 v[10:11], v[10:11], v[0:1]
	global_load_dwordx2 v[0:1], v[14:15], off
	v_pk_add_f32 v[8:9], v[8:9], v[2:3]
	s_waitcnt vmcnt(0) lgkmcnt(0)
	v_lshlrev_b32_e32 v2, 16, v0
	v_and_b32_e32 v3, 0xffff0000, v0
	v_lshlrev_b32_e32 v16, 16, v1
	v_and_b32_e32 v17, 0xffff0000, v1
	v_pk_add_f32 v[0:1], v[6:7], v[2:3]
	v_pk_add_f32 v[2:3], v[4:5], v[16:17]
	v_lshl_add_u64 v[4:5], v[12:13], 2, v[66:67]
	global_store_dwordx4 v[4:5], v[0:3], off
	global_load_dwordx2 v[0:1], v[14:15], off offset:32
	s_waitcnt vmcnt(0) lgkmcnt(0)
	v_lshlrev_b32_e32 v6, 16, v0
	v_and_b32_e32 v7, 0xffff0000, v0
	v_lshlrev_b32_e32 v0, 16, v1
	v_and_b32_e32 v1, 0xffff0000, v1
	v_pk_add_f32 v[2:3], v[8:9], v[0:1]
	v_pk_add_f32 v[0:1], v[10:11], v[6:7]
	global_store_dwordx4 v[4:5], v[0:3], off offset:64
	s_cbranch_scc1 .LBB0_1222
.LBB0_1225:
	s_mov_b64 exec, -1
	v_readlane_b32 s0, v246, 24
	v_mov_b32_e32 v16, v222
	v_readlane_b32 s1, v246, 25
	s_and_b64 vcc, exec, s[0:1]
	v_readfirstlane_b32 s0, v16
	s_cbranch_vccnz .LBB0_1249
	v_lshlrev_b32_e32 v0, 4, v16
	v_add_u32_e32 v1, 0x2000, v0
	v_ashrrev_i32_e32 v2, 31, v1
	v_lshrrev_b32_e32 v2, 22, v2
	v_add_u32_e32 v2, v1, v2
	v_ashrrev_i32_e32 v8, 10, v2
	v_mul_i32_i24_e32 v2, 0x400, v8
	v_sub_u32_e32 v1, v1, v2
	v_lshrrev_b32_e32 v2, 4, v1
	v_bitop3_b32 v1, v2, v1, 32 bitop3:0x6c
	v_ashrrev_i32_e32 v2, 31, v1
	v_lshrrev_b32_e32 v2, 26, v2
	v_add_u32_e32 v2, v1, v2
	v_lshlrev_b32_e32 v3, 3, v8
	v_ashrrev_i32_e32 v9, 6, v2
	v_and_b32_e32 v3, -16, v3
	v_add_u32_e32 v3, v9, v3
	v_and_b32_e32 v4, 3, v9
	s_mov_b32 s3, 0xffffe0
	v_lshrrev_b32_e32 v5, 2, v3
	v_lshlrev_b32_e32 v6, 1, v3
	v_and_b32_e32 v2, 0xc0, v2
	v_and_or_b32 v4, v3, s3, v4
	v_and_b32_e32 v5, 4, v5
	v_and_b32_e32 v6, 24, v6
	v_sub_u32_e32 v1, v1, v2
	v_or3_b32 v4, v4, v5, v6
	v_lshlrev_b32_e32 v5, 5, v8
	v_ashrrev_i16_sdwa v1, v224, sext(v1) dst_sel:DWORD dst_unused:UNUSED_PAD src0_sel:DWORD src1_sel:BYTE_0
	v_and_b32_e32 v10, 32, v5
	v_bfe_i32 v11, v1, 0, 16
	s_movk_i32 s2, 0xb00
	v_mul_u32_u24_e32 v4, 0xb00, v4
	v_add_u32_e32 v1, v10, v11
	v_mul_lo_u32 v2, v3, s2
	v_add_lshl_u32 v206, v4, v1, 1
	v_add_lshl_u32 v208, v1, v2, 1
	v_bfe_i32 v1, v16, 27, 1
	v_lshrrev_b32_e32 v1, 22, v1
	v_add_u32_e32 v1, v0, v1
	v_and_b32_e32 v1, 0xfffffc00, v1
	v_sub_u32_e32 v0, v0, v1
	v_lshrrev_b32_e32 v1, 4, v0
	v_ashrrev_i32_e32 v2, 31, v16
	v_bitop3_b32 v0, v1, v0, 32 bitop3:0x6c
	v_lshrrev_b32_e32 v2, 26, v2
	v_ashrrev_i32_e32 v1, 31, v0
	v_add_u32_e32 v2, v16, v2
	v_lshrrev_b32_e32 v1, 26, v1
	v_ashrrev_i32_e32 v13, 6, v2
	v_add_u32_e32 v1, v0, v1
	v_lshlrev_b32_e32 v2, 3, v13
	v_ashrrev_i32_e32 v12, 6, v1
	v_and_b32_e32 v2, -16, v2
	v_add_u32_e32 v2, v12, v2
	v_and_b32_e32 v3, 3, v12
	v_lshrrev_b32_e32 v4, 2, v2
	v_lshlrev_b32_e32 v5, 1, v2
	v_and_b32_e32 v1, 0xc0, v1
	s_ashr_i32 s1, s0, 6
	v_and_or_b32 v3, v2, s3, v3
	v_and_b32_e32 v4, 4, v4
	v_and_b32_e32 v5, 24, v5
	v_sub_u32_e32 v0, v0, v1
	s_ashr_i32 s8, s0, 8
	s_lshl_b32 s7, s1, 10
	v_or3_b32 v3, v3, v4, v5
	v_lshlrev_b32_e32 v4, 5, v13
	v_ashrrev_i16_sdwa v0, v224, sext(v0) dst_sel:DWORD dst_unused:UNUSED_PAD src0_sel:DWORD src1_sel:BYTE_0
	v_mul_lo_u32 v1, v2, s2
	v_readlane_b32 s2, v247, 55
	v_and_b32_e32 v14, 32, v4
	v_bfe_i32 v15, v0, 0, 16
	s_add_u32 s14, s22, s2
	v_readlane_b32 s2, v247, 53
	v_mul_u32_u24_e32 v3, 0xb00, v3
	v_add_u32_e32 v0, v14, v15
	s_addc_u32 s15, s23, s2
	s_add_i32 s20, s7, 0
	v_add_lshl_u32 v210, v3, v0, 1
	s_add_i32 m0, s20, 0x10000
	v_add_lshl_u32 v212, v0, v1, 1
	global_load_lds_dwordx4 v210, s[14:15]
	s_add_i32 m0, s20, 0x12000
	s_add_u32 s2, s14, 0xb0000
	global_load_lds_dwordx4 v206, s[14:15]
	s_addc_u32 s3, s15, 0
	s_add_i32 m0, s20, 0x14000
	v_mov_b32_e32 v211, v97
	global_load_lds_dwordx4 v210, s[2:3]
	s_add_i32 m0, s20, 0x16000
	v_mov_b32_e32 v207, v97
	global_load_lds_dwordx4 v206, s[2:3]
	v_readlane_b32 s2, v247, 52
	s_add_u32 s12, s84, s2
	v_readlane_b32 s2, v247, 47
	s_addc_u32 s13, s85, s2
	s_add_i32 s21, s20, 0x2000
	s_mov_b32 m0, s20
	s_add_u32 s2, s12, 0xb0000
	global_load_lds_dwordx4 v212, s[12:13]
	s_mov_b32 m0, s21
	s_addc_u32 s3, s13, 0
	s_add_i32 s25, s20, 0x4000
	global_load_lds_dwordx4 v208, s[12:13]
	s_mov_b32 m0, s25
	s_add_i32 s27, s20, 0x6000
	global_load_lds_dwordx4 v212, s[2:3]
	s_mov_b32 m0, s27
	v_mov_b32_e32 v213, v97
	global_load_lds_dwordx4 v208, s[2:3]
	v_mov_b32_e32 v209, v97
	s_cmp_eq_u32 s8, 1
	v_lshl_add_u64 v[6:7], s[14:15], 0, v[210:211]
	v_lshl_add_u64 v[4:5], s[14:15], 0, v[206:207]
	v_lshl_add_u64 v[0:1], s[12:13], 0, v[212:213]
	s_cselect_b64 s[2:3], -1, 0
	s_cmp_lg_u32 s8, 1
	v_lshl_add_u64 v[2:3], s[12:13], 0, v[208:209]
	s_cbranch_scc1 .LBB0_1228
	s_barrier

; #define LAS __attribute__((address_space(3)))
; __device__ __forceinline__ SmallId small_id() { int tid = threadIdx.x; asm volatile("" : "+v"(tid)); SmallId i; i.w = __builtin_amdgcn_readfirstlane(tid >> 6); i.fr = tid & 15; i.fq = (tid & 63) >> 4; i.row = MP + 16 * i.w + i.fr; return i; }
; template <int KSTEPS  >
; __device__ __forceinline__ void small_mma_ksplit(f32x4 (&acc)[2], const bf16_t* A, int lda, const bf16_t* Bt, int ldb, int n0, LAS unsigned char* lds, const SmallId& id) {
;     const int lane = id.fq * 16 + id.fr, k0 = id.w * (KSTEPS * 32);
;     f32x4 part[8][2];
; #pragma unroll
;     for (int rb = 0; rb < 8; ++rb) { part[rb][0] = (f32x4){0.f, 0.f, 0.f, 0.f}; part[rb][1] = part[rb][0]; }
;     const bf16_t* ap = A + (size_t)(MP + id.fr) * lda + k0 + 8 * id.fq;
;     const bf16_t* bp = Bt + (size_t)(n0 + id.fr) * ldb + k0 + 8 * id.fq;
; template <bool RES_F32, bool OUT_F32, int KSTEPS>
; __device__ __forceinline__ void small_res(const Params& p, LAS unsigned char* lds, const bf16_t* A, int lda, const bf16_t* Bt, int K, float* ssq_next, int G, int bx) {
;     const SmallId id = small_id();
;     bf16_t* XB = (bf16_t*)(p.ws + WS_XB);
;     for (int ts = G - 1 - bx; ts < DM / 32; ts += G) {
;         const int n0 = ts * 32; f32x4 acc[2] = {(f32x4){0.f, 0.f, 0.f, 0.f}, (f32x4){0.f, 0.f, 0.f, 0.f}};
;         small_mma_ksplit<KSTEPS>(acc, A, lda, Bt, K, n0, lds, id);
;         float s = 0.f;
; #pragma unroll
;         for (int nb = 0; nb < 2; ++nb) { const int col = n0 + 16 * nb + 4 * id.fq;
.LBB0_1250:
	s_and_b64 vcc, exec, s[0:1]
	s_cbranch_vccz .LBB0_1298
	v_readlane_b32 s0, v246, 22
	s_add_u32 s2, s86, 0x40800
	v_mov_b32_e32 v0, v222
	v_readlane_b32 s1, v246, 23
	s_addc_u32 s3, s87, 0
	s_and_b64 vcc, exec, s[0:1]
	v_readfirstlane_b32 s0, v0
	s_ashr_i32 s7, s0, 6
	s_lshl_b32 s0, s7, 4
	v_and_b32_e32 v4, 15, v0
	s_add_i32 s0, s0, 0x8000
	v_or_b32_e32 v2, s0, v4
	v_bfe_u32 v5, v0, 4, 2
	s_mul_i32 s0, s7, 0x160
	s_lshl_b32 s8, s7, 14
	v_lshlrev_b32_e32 v0, 4, v0
	s_lshl_b32 s7, s7, 11
	s_add_i32 s8, s8, 0
	v_and_b32_e32 v0, 0x3f0, v0
	s_add_i32 s7, s7, 0
	v_add_u32_e32 v74, s8, v0
	s_add_i32 s8, s7, 0x10400
	s_ashr_i32 s1, s0, 31
	v_add_u32_e32 v77, s8, v0
	s_add_i32 s8, s7, 0x14400
	v_add_u32_e32 v75, s7, v0
	v_add_u32_e32 v79, s8, v0
	s_add_i32 s8, s7, 0x18400
	s_add_i32 s7, s7, 0x1c400
	s_lshl_b64 s[0:1], s[0:1], 1
	v_add_u32_e32 v83, s7, v0
	s_add_u32 s7, s86, s0
	v_add_u32_e32 v81, s8, v0
	v_ashrrev_i32_e32 v3, 31, v2
	s_addc_u32 s9, s87, s1
	v_readlane_b32 s8, v246, 15
	v_lshlrev_b64 v[0:1], 11, v[2:3]
	s_add_u32 s8, s7, s8
	v_lshl_add_u64 v[64:65], s[90:91], 0, v[0:1]
	v_lshlrev_b32_e32 v0, 4, v5
	v_mov_b32_e32 v1, v97
	s_addc_u32 s9, s9, 0
	v_mul_u32_u24_e32 v96, 0x1600, v4
	v_lshl_add_u64 v[68:69], s[8:9], 0, v[0:1]
	v_or_b32_e32 v0, s0, v0
	v_mov_b32_e32 v1, s1
	v_readlane_b32 s7, v246, 8
	s_lshr_b32 s7, s7, 3
	s_lshl_b32 s7, s7, 5
	v_lshl_add_u64 v[0:1], v[0:1], 0, v[96:97]
	v_add_u32_e32 v76, 0x10000, v75
	v_add_u32_e32 v78, 0x14000, v75
	v_add_u32_e32 v80, 0x18000, v75
	v_add_u32_e32 v82, 0x1c000, v75
	v_lshlrev_b32_e32 v84, 2, v5
	v_cmp_eq_u32_e32 vcc, 0, v5
	v_lshl_add_u64 v[66:67], v[2:3], 2, s[2:3]
	v_add_u32_e32 v85, s7, v4
	v_lshl_add_u64 v[70:71], s[86:87], 0, v[0:1]
	v_readlane_b32 s7, v246, 8
	s_lshr_b32 s7, s7, 3
	s_branch .LBB0_1254

; #define LAS __attribute__((address_space(3)))
; template <int KSTEPS  >
; __device__ __forceinline__ void small_mma_ksplit(f32x4 (&acc)[2], const bf16_t* A, int lda, const bf16_t* Bt, int ldb, int n0, LAS unsigned char* lds, const SmallId& id) {
;     const int lane = id.fq * 16 + id.fr, k0 = id.w * (KSTEPS * 32);
;     f32x4 part[8][2];
; #pragma unroll
;     for (int rb = 0; rb < 8; ++rb) { part[rb][0] = (f32x4){0.f, 0.f, 0.f, 0.f}; part[rb][1] = part[rb][0]; }
;     const bf16_t* ap = A + (size_t)(MP + id.fr) * lda + k0 + 8 * id.fq;
;     const bf16_t* bp = Bt + (size_t)(n0 + id.fr) * ldb + k0 + 8 * id.fq;
; #pragma unroll 1
;     for (int ks = 0; ks < KSTEPS; ++ks) {
;         bf16x8 a[8], b[2];
; #pragma unroll
;         for (int rb = 0; rb < 8; ++rb) a[rb] = *(const bf16x8*)(ap + (size_t)(16 * rb) * lda + 32 * ks);
;         b[0] = *(const bf16x8*)(bp + 32 * ks); b[1] = *(const bf16x8*)(bp + (size_t)16 * ldb + 32 * ks);
; #pragma unroll
;         for (int rb = 0; rb < 8; ++rb) { part[rb][0] = __builtin_amdgcn_mfma_f32_16x16x32_bf16(b[0], a[rb], part[rb][0], 0, 0, 0); part[rb][1] = __builtin_amdgcn_mfma_f32_16x16x32_bf16(b[1], a[rb], part[rb][1], 0, 0, 0); }
;     }
;     LAS f32x4* red = (LAS f32x4*)lds;
; #pragma unroll
;     for (int rb = 0; rb < 8; ++rb) { red[((id.w * 8 + rb) * 2 + 0) * 64 + lane] = part[rb][0]; red[((id.w * 8 + rb) * 2 + 1) * 64 + lane] = part[rb][1]; }
;     asm volatile("s_waitcnt lgkmcnt(0)" ::: "memory"); __syncthreads();
;     acc[0] = (f32x4){0.f, 0.f, 0.f, 0.f}; acc[1] = acc[0];
; #pragma unroll
;     for (int w2 = 0; w2 < 8; ++w2) { acc[0] += red[((w2 * 8 + id.w) * 2 + 0) * 64 + lane]; acc[1] += red[((w2 * 8 + id.w) * 2 + 1) * 64 + lane]; }
;     asm volatile("s_waitcnt lgkmcnt(0)" ::: "memory"); __syncthreads();
.LBB0_1255:
	s_waitcnt lgkmcnt(0)
	v_readlane_b32 s8, v246, 8
	v_readfirstlane_b32 s32, v222
	s_and_b32 s8, s8, 7
	s_lshr_b32 s32, s32, 6
	s_cmp_eq_u32 s32, s8
	s_cselect_b32 s32, 1, 0
	s_lshl_b32 s9, s8, 11
	v_add_u32_e32 v68, s9, v74
	s_sub_i32 s9, s53, s52
	s_mul_i32 s8, s8, s9
	s_add_i32 s8, s8, s52
	s_mov_b32 s9, 0
	v_lshl_add_u64 v[86:87], v[70:71], 0, s[8:9]
	s_mov_b32 s8, s62
	v_lshl_add_u64 v[88:89], v[72:73], 0, s[8:9]
	s_mov_b32 s8, s63
	v_lshl_add_u64 v[90:91], v[72:73], 0, s[8:9]
	global_load_dwordx4 v[92:95], v[86:87], off
	global_load_dwordx4 v[98:101], v[88:89], off
	global_load_dwordx4 v[102:105], v[90:91], off
	global_load_dwordx4 v[106:109], v[86:87], off offset:64
	global_load_dwordx4 v[110:113], v[88:89], off offset:64
	global_load_dwordx4 v[114:117], v[90:91], off offset:64
	global_load_dwordx4 v[118:121], v[86:87], off offset:128
	global_load_dwordx4 v[122:125], v[88:89], off offset:128
	global_load_dwordx4 v[126:129], v[90:91], off offset:128
	global_load_dwordx4 v[130:133], v[86:87], off offset:192
	global_load_dwordx4 v[134:137], v[88:89], off offset:192
	global_load_dwordx4 v[138:141], v[90:91], off offset:192
	global_load_dwordx4 v[142:145], v[86:87], off offset:256
	global_load_dwordx4 v[146:149], v[88:89], off offset:256
	global_load_dwordx4 v[150:153], v[90:91], off offset:256
	global_load_dwordx4 v[154:157], v[86:87], off offset:320
	global_load_dwordx4 v[158:161], v[88:89], off offset:320
	global_load_dwordx4 v[162:165], v[90:91], off offset:320
	global_load_dwordx4 v[166:169], v[86:87], off offset:384
	global_load_dwordx4 v[170:173], v[88:89], off offset:384
	global_load_dwordx4 v[174:177], v[90:91], off offset:384
	global_load_dwordx4 v[178:181], v[86:87], off offset:448
	global_load_dwordx4 v[182:185], v[88:89], off offset:448
	global_load_dwordx4 v[186:189], v[90:91], off offset:448
	s_waitcnt vmcnt(21)
	v_mfma_f32_16x16x32_bf16 v[36:39], v[98:101], v[92:95], v[36:39]
	v_mfma_f32_16x16x32_bf16 v[24:27], v[102:105], v[92:95], v[24:27]
	global_load_dwordx4 v[92:95], v[86:87], off offset:512
	global_load_dwordx4 v[98:101], v[88:89], off offset:512
	global_load_dwordx4 v[102:105], v[90:91], off offset:512
	s_waitcnt vmcnt(21)
	v_mfma_f32_16x16x32_bf16 v[36:39], v[110:113], v[106:109], v[36:39]
	v_mfma_f32_16x16x32_bf16 v[24:27], v[114:117], v[106:109], v[24:27]
	global_load_dwordx4 v[106:109], v[86:87], off offset:576
	global_load_dwordx4 v[110:113], v[88:89], off offset:576
	global_load_dwordx4 v[114:117], v[90:91], off offset:576
	s_waitcnt vmcnt(21)
	v_mfma_f32_16x16x32_bf16 v[36:39], v[122:125], v[118:121], v[36:39]
	v_mfma_f32_16x16x32_bf16 v[24:27], v[126:129], v[118:121], v[24:27]
	global_load_dwordx4 v[118:121], v[86:87], off offset:640
	global_load_dwordx4 v[122:125], v[88:89], off offset:640
	global_load_dwordx4 v[126:129], v[90:91], off offset:640
	s_waitcnt vmcnt(21)
	v_mfma_f32_16x16x32_bf16 v[36:39], v[134:137], v[130:133], v[36:39]
	v_mfma_f32_16x16x32_bf16 v[24:27], v[138:141], v[130:133], v[24:27]
	s_waitcnt vmcnt(18)
	v_mfma_f32_16x16x32_bf16 v[36:39], v[146:149], v[142:145], v[36:39]
	v_mfma_f32_16x16x32_bf16 v[24:27], v[150:153], v[142:145], v[24:27]
	s_waitcnt vmcnt(15)
	v_mfma_f32_16x16x32_bf16 v[36:39], v[158:161], v[154:157], v[36:39]
	v_mfma_f32_16x16x32_bf16 v[24:27], v[162:165], v[154:157], v[24:27]
	s_waitcnt vmcnt(12)
	v_mfma_f32_16x16x32_bf16 v[36:39], v[170:173], v[166:169], v[36:39]
	v_mfma_f32_16x16x32_bf16 v[24:27], v[174:177], v[166:169], v[24:27]
	s_waitcnt vmcnt(9)
	v_mfma_f32_16x16x32_bf16 v[36:39], v[182:185], v[178:181], v[36:39]
	v_mfma_f32_16x16x32_bf16 v[24:27], v[186:189], v[178:181], v[24:27]
	s_waitcnt vmcnt(6)
	v_mfma_f32_16x16x32_bf16 v[36:39], v[98:101], v[92:95], v[36:39]
	v_mfma_f32_16x16x32_bf16 v[24:27], v[102:105], v[92:95], v[24:27]
	s_waitcnt vmcnt(3)
	v_mfma_f32_16x16x32_bf16 v[36:39], v[110:113], v[106:109], v[36:39]
	v_mfma_f32_16x16x32_bf16 v[24:27], v[114:117], v[106:109], v[24:27]
	s_waitcnt vmcnt(0)
	v_mfma_f32_16x16x32_bf16 v[36:39], v[122:125], v[118:121], v[36:39]
	v_mfma_f32_16x16x32_bf16 v[24:27], v[126:129], v[118:121], v[24:27]
	s_nop 7
	s_nop 1
	ds_write_b128 v68, v[36:39]
	ds_write_b128 v68, v[24:27] offset:1024
	s_waitcnt lgkmcnt(0)
	s_waitcnt lgkmcnt(0)
	s_barrier
	ds_read_b128 v[0:3], v75
	s_waitcnt lgkmcnt(0)
	v_pk_add_f32 v[4:5], v[2:3], 0 op_sel_hi:[1,0]
	v_pk_add_f32 v[6:7], v[0:1], 0 op_sel_hi:[1,0]
	ds_read_b128 v[0:3], v75 offset:1024
	s_waitcnt lgkmcnt(0)
	v_pk_add_f32 v[8:9], v[2:3], 0 op_sel_hi:[1,0]
	v_pk_add_f32 v[10:11], v[0:1], 0 op_sel_hi:[1,0]
	ds_read_b128 v[0:3], v75 offset:16384
	s_waitcnt lgkmcnt(0)
	v_pk_add_f32 v[4:5], v[4:5], v[2:3]
	v_pk_add_f32 v[6:7], v[6:7], v[0:1]
	ds_read_b128 v[0:3], v75 offset:17408
	s_waitcnt lgkmcnt(0)
	v_pk_add_f32 v[8:9], v[8:9], v[2:3]
	v_pk_add_f32 v[10:11], v[10:11], v[0:1]
	ds_read_b128 v[0:3], v75 offset:32768
	s_waitcnt lgkmcnt(0)
	v_pk_add_f32 v[4:5], v[4:5], v[2:3]
	v_pk_add_f32 v[6:7], v[6:7], v[0:1]
	ds_read_b128 v[0:3], v75 offset:33792
	s_waitcnt lgkmcnt(0)
	v_pk_add_f32 v[8:9], v[8:9], v[2:3]
	v_pk_add_f32 v[10:11], v[10:11], v[0:1]
	ds_read_b128 v[0:3], v75 offset:49152
	s_waitcnt lgkmcnt(0)
	v_pk_add_f32 v[4:5], v[4:5], v[2:3]
	v_pk_add_f32 v[6:7], v[6:7], v[0:1]
	ds_read_b128 v[0:3], v75 offset:50176
	s_waitcnt lgkmcnt(0)
	v_pk_add_f32 v[8:9], v[8:9], v[2:3]
	v_pk_add_f32 v[10:11], v[10:11], v[0:1]
	ds_read_b128 v[0:3], v76
	s_waitcnt lgkmcnt(0)
	v_pk_add_f32 v[4:5], v[4:5], v[2:3]
	v_pk_add_f32 v[6:7], v[6:7], v[0:1]
	ds_read_b128 v[0:3], v77
	s_waitcnt lgkmcnt(0)
	v_pk_add_f32 v[8:9], v[8:9], v[2:3]
	v_pk_add_f32 v[10:11], v[10:11], v[0:1]
	ds_read_b128 v[0:3], v78
	s_waitcnt lgkmcnt(0)
	v_pk_add_f32 v[4:5], v[4:5], v[2:3]
	v_pk_add_f32 v[6:7], v[6:7], v[0:1]
	ds_read_b128 v[0:3], v79
	s_waitcnt lgkmcnt(0)
	v_pk_add_f32 v[8:9], v[8:9], v[2:3]
	v_pk_add_f32 v[10:11], v[10:11], v[0:1]
	ds_read_b128 v[0:3], v80
	s_waitcnt lgkmcnt(0)
	v_pk_add_f32 v[4:5], v[4:5], v[2:3]
	v_pk_add_f32 v[6:7], v[6:7], v[0:1]
	ds_read_b128 v[0:3], v81
	s_waitcnt lgkmcnt(0)
	v_pk_add_f32 v[8:9], v[8:9], v[2:3]
	v_pk_add_f32 v[10:11], v[10:11], v[0:1]
	ds_read_b128 v[0:3], v82
	s_waitcnt lgkmcnt(0)
	v_pk_add_f32 v[4:5], v[4:5], v[2:3]
	v_pk_add_f32 v[6:7], v[6:7], v[0:1]
	ds_read_b128 v[0:3], v83
	s_waitcnt lgkmcnt(0)
	s_waitcnt lgkmcnt(0)
	s_barrier
;     __device__ __forceinline__ bool next(int i, Unit& u) const { u.z = 0; return o.tile(i, u); }
; template <class Epi, class Sched>
; __device__ __forceinline__ void gemm_phase(LAS unsigned char* lds, const Gemm g, const Sched& S, const Epi& E) {
;     ...
;     for (int i = 0; i < 2; ++i) { int R, C; stage_rc(tid * 16 + i * 8192, R, C); const int Rb = Epi::PERM ? ((R & ~31) + perm32(R & 31)) : R;
;         voffA[i] = (unsigned)(R * g.lda + C) * 2u; voffB[i] = (unsigned)(Rb * g.ldb + C) * 2u; }
;     const size_t kstep = (size_t)(BK * 2);
;     const size_t hstepA = (size_t)HALF * g.lda * 2, hstepB = (size_t)HALF * g.ldb * 2;
;     const unsigned ldsw = (unsigned)wid * 1024u;
;     const int aoff = lds_byte(wr * 64 + fr, fq * 8), boff = lds_byte(wc * 32 + fr, fq * 8);
;     ...
;     Unit cur, nxt; int ui = 0;
;     if (!S.next(0, cur)) return;
;     f32x4 acc[2][2][4][2];
; #pragma unroll
;     for (int a = 0; a < 2; ++a)
; #pragma unroll
;         for (int b = 0; b < 2; ++b)
; #pragma unroll
;             for (int m = 0; m < 4; ++m)
; #pragma unroll
;                 for (int n = 0; n < 2; ++n) acc[a][b][m][n] = (f32x4){0.f, 0.f, 0.f, 0.f};
;     bf16x8 At[4][2], B0[2][2], B1[2][2];
;     const char* cA = (const char*)g.A + S.a_off(cur); const char* cB = (const char*)g.Bt + S.b_off(cur);
; template <bool RES_F32, bool OUT_F32, int KSTEPS>
; __device__ __forceinline__ void small_res(const Params& p, LAS unsigned char* lds, const bf16_t* A, int lda, const bf16_t* Bt, int K, float* ssq_next, int G, int bx) {
;     ...
;         float s = 0.f;
; #pragma unroll
;         for (int nb = 0; nb < 2; ++nb) { const int col = n0 + 16 * nb + 4 * id.fq;
;             f32x4 r;
;             if (RES_F32) r = *(const f32x4*)(p.xs + (size_t)(id.row - MP) * DM + col);
;             else { const u32x2 w = *(const u32x2*)(XB + (size_t)id.row * DM + col); r = (f32x4){bf_lo(w.x), bf_hi(w.x), bf_lo(w.y), bf_hi(w.y)}; }
;             const f32x4 x = r + acc[nb];
;             if (OUT_F32) *(f32x4*)(p.out + (size_t)id.row * DM + col) = x;
;             else { u32x2 w; w.x = cvt_pk_bf16(x[0], x[1]); w.y = cvt_pk_bf16(x[2], x[3]); *(u32x2*)(XB + (size_t)id.row * DM + col) = w; }
;             s += (x[0] * x[0] + x[1] * x[1]) + (x[2] * x[2] + x[3] * x[3]); }
;         if (!OUT_F32) { s += __shfl_xor(s, 16); s += __shfl_xor(s, 32); if (id.fq == 0) atomicAdd(ssq_next + id.row, s); }
;     }
	s_mul_i32 exec_lo, s32, -1
	s_mov_b32 exec_hi, exec_lo
	v_pk_add_f32 v[2:3], v[8:9], v[2:3]
	v_lshl_or_b32 v8, s7, 5, v84
	v_ashrrev_i32_e32 v9, 31, v8
	v_lshl_add_u64 v[8:9], v[8:9], 1, v[64:65]
	v_pk_add_f32 v[0:1], v[10:11], v[0:1]
	global_load_dwordx2 v[10:11], v[8:9], off
	s_waitcnt vmcnt(0) lgkmcnt(0)
	v_lshlrev_b32_e32 v12, 16, v10
	v_and_b32_e32 v13, 0xffff0000, v10
	v_lshlrev_b32_e32 v10, 16, v11
	v_and_b32_e32 v11, 0xffff0000, v11
	v_pk_add_f32 v[4:5], v[4:5], v[10:11]
	v_pk_add_f32 v[6:7], v[6:7], v[12:13]
	s_nop 0
	v_cvt_pk_bf16_f32 v10, v6, v7
	v_cvt_pk_bf16_f32 v11, v4, v5
	v_mul_f32_e32 v7, v7, v7
	v_mul_f32_e32 v5, v5, v5
	v_fmac_f32_e32 v7, v6, v6
	v_fmac_f32_e32 v5, v4, v4
	global_store_dwordx2 v[8:9], v[10:11], off
	v_add_f32_e32 v10, v7, v5
	global_load_dwordx2 v[4:5], v[8:9], off offset:32
	s_waitcnt vmcnt(0) lgkmcnt(0)
	v_lshlrev_b32_e32 v6, 16, v4
	v_and_b32_e32 v7, 0xffff0000, v4
	v_lshlrev_b32_e32 v4, 16, v5
	v_and_b32_e32 v5, 0xffff0000, v5
	v_pk_add_f32 v[0:1], v[0:1], v[6:7]
	v_pk_add_f32 v[2:3], v[2:3], v[4:5]
	v_cvt_pk_bf16_f32 v4, v0, v1
	v_mul_f32_e32 v1, v1, v1
	v_fmac_f32_e32 v1, v0, v0
	v_mul_f32_e32 v0, v3, v3
	v_cvt_pk_bf16_f32 v5, v2, v3
	v_fmac_f32_e32 v0, v2, v2
	v_and_b32_e32 v2, 64, v225
	v_add_f32_e32 v0, v1, v0
	v_xor_b32_e32 v1, 16, v225
	v_add_u32_e32 v2, 64, v2
	v_cmp_lt_i32_e64 s[0:1], v1, v2
	v_add_f32_e32 v0, v10, v0
	global_store_dwordx2 v[8:9], v[4:5], off offset:32
	v_cndmask_b32_e64 v1, v225, v1, s[0:1]
	v_lshlrev_b32_e32 v1, 2, v1
	ds_bpermute_b32 v1, v1, v0
	s_waitcnt lgkmcnt(0)
	v_add_f32_e32 v0, v0, v1
	v_xor_b32_e32 v1, 32, v225
	v_cmp_lt_i32_e64 s[0:1], v1, v2
	s_nop 1
	v_cndmask_b32_e64 v1, v225, v1, s[0:1]
	v_lshlrev_b32_e32 v1, 2, v1
	ds_bpermute_b32 v1, v1, v0
	s_and_saveexec_b64 s[0:1], vcc
	s_cbranch_execz .LBB0_1253
	s_waitcnt lgkmcnt(0)
	v_add_f32_e32 v0, v0, v1
	global_atomic_add_f32 v[66:67], v0, off
	s_branch .LBB0_1253
.LBB0_1258:
	s_mov_b64 exec, -1
	v_readlane_b32 s0, v246, 24
	v_mov_b32_e32 v16, v222
	v_readlane_b32 s1, v246, 25
	s_and_b64 vcc, exec, s[0:1]
	v_readfirstlane_b32 s0, v16
	s_cbranch_vccnz .LBB0_1298
	v_lshlrev_b32_e32 v0, 4, v16
	s_waitcnt lgkmcnt(0)
	v_add_u32_e32 v1, 0x2000, v0
	v_ashrrev_i32_e32 v2, 31, v1
	v_lshrrev_b32_e32 v2, 22, v2
	v_add_u32_e32 v2, v1, v2
	v_ashrrev_i32_e32 v8, 10, v2
	v_mul_i32_i24_e32 v2, 0x400, v8
	v_sub_u32_e32 v1, v1, v2
	v_lshrrev_b32_e32 v2, 4, v1
	v_bitop3_b32 v1, v2, v1, 32 bitop3:0x6c
	v_ashrrev_i32_e32 v2, 31, v1
	v_lshrrev_b32_e32 v2, 26, v2
	v_add_u32_e32 v2, v1, v2
	v_lshlrev_b32_e32 v3, 3, v8
	v_ashrrev_i32_e32 v9, 6, v2
	v_and_b32_e32 v3, -16, v3
	v_add_u32_e32 v3, v9, v3
	v_and_b32_e32 v4, 3, v9
	s_mov_b32 s9, 0xffffe0
	v_lshrrev_b32_e32 v5, 2, v3
	v_lshlrev_b32_e32 v6, 1, v3
	v_and_b32_e32 v2, 0xc0, v2
	v_and_or_b32 v4, v3, s9, v4
	v_and_b32_e32 v5, 4, v5
	v_and_b32_e32 v6, 24, v6
	v_sub_u32_e32 v1, v1, v2
	v_or3_b32 v4, v4, v5, v6
	v_lshlrev_b32_e32 v5, 5, v8
	v_ashrrev_i16_sdwa v1, v224, sext(v1) dst_sel:DWORD dst_unused:UNUSED_PAD src0_sel:DWORD src1_sel:BYTE_0
	v_and_b32_e32 v10, 32, v5
	v_bfe_i32 v11, v1, 0, 16
	s_movk_i32 s8, 0xb00
	v_mul_u32_u24_e32 v4, 0xb00, v4
	v_add_u32_e32 v1, v10, v11
	v_mul_lo_u32 v2, v3, s8
	v_add_lshl_u32 v206, v4, v1, 1
	v_add_lshl_u32 v208, v1, v2, 1
	v_bfe_i32 v1, v16, 27, 1
	v_lshrrev_b32_e32 v1, 22, v1
	v_add_u32_e32 v1, v0, v1
	v_and_b32_e32 v1, 0xfffffc00, v1
	v_sub_u32_e32 v0, v0, v1
	v_lshrrev_b32_e32 v1, 4, v0
	v_ashrrev_i32_e32 v2, 31, v16
	v_bitop3_b32 v0, v1, v0, 32 bitop3:0x6c
	v_lshrrev_b32_e32 v2, 26, v2
	v_ashrrev_i32_e32 v1, 31, v0
	v_add_u32_e32 v2, v16, v2
	v_lshrrev_b32_e32 v1, 26, v1
	v_ashrrev_i32_e32 v13, 6, v2
	v_add_u32_e32 v1, v0, v1
	v_lshlrev_b32_e32 v2, 3, v13
	v_ashrrev_i32_e32 v12, 6, v1
	v_and_b32_e32 v2, -16, v2
	v_add_u32_e32 v2, v12, v2
	v_and_b32_e32 v3, 3, v12
	v_lshrrev_b32_e32 v4, 2, v2
	v_lshlrev_b32_e32 v5, 1, v2
	v_and_b32_e32 v1, 0xc0, v1
	s_ashr_i32 s1, s0, 6
	v_and_or_b32 v3, v2, s9, v3
	v_and_b32_e32 v4, 4, v4
	v_and_b32_e32 v5, 24, v5
	v_sub_u32_e32 v0, v0, v1
	s_ashr_i32 s10, s0, 8
	s_lshl_b32 s7, s1, 10
	v_or3_b32 v3, v3, v4, v5
	v_lshlrev_b32_e32 v4, 5, v13
	v_ashrrev_i16_sdwa v0, v224, sext(v0) dst_sel:DWORD dst_unused:UNUSED_PAD src0_sel:DWORD src1_sel:BYTE_0
	v_mul_lo_u32 v1, v2, s8
	v_readlane_b32 s8, v247, 55
	v_and_b32_e32 v14, 32, v4
	v_bfe_i32 v15, v0, 0, 16
	s_add_u32 s18, s22, s8
	v_readlane_b32 s8, v247, 53
	v_mul_u32_u24_e32 v3, 0xb00, v3
	v_add_u32_e32 v0, v14, v15
	s_addc_u32 s19, s23, s8
	s_add_i32 s25, s7, 0
	v_add_lshl_u32 v210, v3, v0, 1
	s_add_i32 m0, s25, 0x10000
	v_add_lshl_u32 v212, v0, v1, 1
	global_load_lds_dwordx4 v210, s[18:19]
	s_add_i32 m0, s25, 0x12000
	s_add_u32 s8, s18, 0xb0000
	global_load_lds_dwordx4 v206, s[18:19]
	s_addc_u32 s9, s19, 0
	s_add_i32 m0, s25, 0x14000
	v_mov_b32_e32 v211, v97
	global_load_lds_dwordx4 v210, s[8:9]
	s_add_i32 m0, s25, 0x16000
	v_mov_b32_e32 v207, v97
	global_load_lds_dwordx4 v206, s[8:9]
	v_readlane_b32 s8, v247, 52
	s_add_u32 s16, s84, s8
	v_readlane_b32 s8, v247, 47
	s_addc_u32 s17, s85, s8
	s_add_i32 s27, s25, 0x2000
	s_mov_b32 m0, s25
	s_add_u32 s8, s16, 0xb0000
	global_load_lds_dwordx4 v212, s[16:17]
	s_mov_b32 m0, s27
	s_addc_u32 s9, s17, 0
	s_add_i32 s29, s25, 0x4000
	global_load_lds_dwordx4 v208, s[16:17]
	s_mov_b32 m0, s29
	s_add_i32 s31, s25, 0x6000
	global_load_lds_dwordx4 v212, s[8:9]
	s_mov_b32 m0, s31
	v_mov_b32_e32 v213, v97
	global_load_lds_dwordx4 v208, s[8:9]
	v_mov_b32_e32 v209, v97
	s_cmp_eq_u32 s10, 1
	v_lshl_add_u64 v[6:7], s[18:19], 0, v[210:211]
	v_lshl_add_u64 v[4:5], s[18:19], 0, v[206:207]
	v_lshl_add_u64 v[0:1], s[16:17], 0, v[212:213]
	s_cselect_b64 s[8:9], -1, 0
	s_cmp_lg_u32 s10, 1
	v_lshl_add_u64 v[2:3], s[16:17], 0, v[208:209]
	s_cbranch_scc1 .LBB0_1261
	s_barrier
